# v22b + attention step loops: s_setprio decays 3,2,1,0 through each step so the lagging wave of a SIMD pair gets priority
# speedup vs baseline: 1.0093x; 1.0093x over previous
.LBB0_383:
	s_setprio 3
	s_add_i32 s56, s5, s29
	s_add_i32 s3, s56, -3
	s_ashr_i32 s58, s3, 2
	s_ashr_i32 s59, s58, 31
	s_and_b32 s3, s3, 3
	s_lshl_b64 s[58:59], s[58:59], 21
	s_mul_i32 s78, s3, 0x38000
	s_add_i32 s3, s30, 0
	v_lshl_add_u64 v[80:81], v[152:153], 0, s[58:59]
	s_add_i32 s55, s3, s27
	v_lshl_add_u64 v[80:81], v[80:81], 0, s[78:79]
	s_mov_b32 m0, s55
	s_nop 0
	global_load_lds_dwordx4 v[80:81], off
	v_lshl_add_u64 v[80:81], v[156:157], 0, s[58:59]
	v_lshl_add_u64 v[80:81], v[80:81], 0, s[78:79]
	s_add_i32 m0, s55, 0x2000
	s_mov_b32 s55, s53
	global_load_lds_dwordx4 v[80:81], off
	s_mov_b32 s53, s2
	s_add_i32 s2, s55, 0
	v_add_u32_e32 v134, s2, v159
	v_exp_f32_e32 v130, v64
	v_exp_f32_e32 v131, v65
	v_exp_f32_e32 v132, v66
	v_exp_f32_e32 v133, v67
	ds_read_b128 v[64:67], v134
	ds_read_b128 v[114:117], v134 offset:512
	v_exp_f32_e32 v135, v68
	v_add_f32_e32 v68, v3, v7
	v_exp_f32_e32 v136, v69
	s_waitcnt lgkmcnt(0)
	v_mfma_f32_32x32x16_bf16 v[80:95], v[64:67], v[110:113], v[16:31]
	ds_read_b128 v[64:67], v134 offset:2048
	ds_read_b128 v[118:121], v134 offset:2560
	ds_read_b128 v[122:125], v134 offset:4096
	v_exp_f32_e32 v137, v70
	v_exp_f32_e32 v138, v71
	v_exp_f32_e32 v139, v72
	v_exp_f32_e32 v140, v73
	v_exp_f32_e32 v141, v74
	v_exp_f32_e32 v142, v75
	s_waitcnt lgkmcnt(0)
	v_mfma_f32_32x32x16_bf16 v[80:95], v[64:67], v[106:109], v[80:95]
	ds_read_b128 v[126:129], v134 offset:4608
	ds_read_b128 v[64:67], v134 offset:6144
	v_exp_f32_e32 v143, v76
	v_exp_f32_e32 v144, v77
	v_exp_f32_e32 v145, v78
	v_exp_f32_e32 v163, v79
	v_mfma_f32_32x32x16_bf16 v[80:95], v[122:125], v[102:105], v[80:95]
	ds_read_b128 v[122:125], v134 offset:6656
	s_waitcnt lgkmcnt(0)
	v_mfma_f32_32x32x16_bf16 v[80:95], v[64:67], v[98:101], v[80:95]
	v_add_f32_e32 v64, v6, v68
	v_add_f32_e32 v64, v11, v64
	v_add_f32_e32 v64, v10, v64
	v_add_f32_e32 v64, v96, v64
	v_add_f32_e32 v64, v15, v64
	v_add_f32_e32 v64, v97, v64
	v_add_f32_e32 v134, v2, v64
	v_mfma_f32_32x32x16_bf16 v[64:79], v[114:117], v[110:113], v[16:31]
	v_add_f32_e32 v114, v5, v134
	v_add_f32_e32 v114, v4, v114
	v_add_f32_e32 v114, v9, v114
	v_add_f32_e32 v114, v8, v114
	v_add_f32_e32 v114, v12, v114
	v_add_f32_e32 v114, v13, v114
	v_add_f32_e32 v114, v14, v114
	v_mfma_f32_32x32x16_bf16 v[64:79], v[118:121], v[106:109], v[64:79]
	v_add_f32_e32 v114, v130, v114
	v_add_f32_e32 v114, v131, v114
	v_add_f32_e32 v114, v132, v114
	v_add_f32_e32 v114, v133, v114
	v_add_f32_e32 v114, v135, v114
	v_add_f32_e32 v114, v136, v114
	v_add_f32_e32 v114, v137, v114
	v_mfma_f32_32x32x16_bf16 v[64:79], v[126:129], v[102:105], v[64:79]
	v_add_f32_e32 v114, v138, v114
	v_add_f32_e32 v114, v139, v114
	v_add_f32_e32 v114, v140, v114
	v_add_f32_e32 v114, v141, v114
	v_add_f32_e32 v114, v142, v114
	v_add_f32_e32 v114, v143, v114
	v_add_f32_e32 v114, v144, v114
	v_mfma_f32_32x32x16_bf16 v[64:79], v[122:125], v[98:101], v[64:79]
	v_cvt_pk_bf16_f32 v116, v10, v96
	v_cvt_pk_bf16_f32 v10, v2, v5
	v_cvt_pk_bf16_f32 v2, v139, v140
	v_add_f32_e32 v168, v145, v114
	v_cvt_pk_bf16_f32 v114, v3, v7
	v_cvt_pk_bf16_f32 v115, v6, v11
	v_cvt_pk_bf16_f32 v117, v15, v97
	v_cvt_pk_bf16_f32 v11, v4, v9
	v_cvt_pk_bf16_f32 v12, v8, v12
	v_cvt_pk_bf16_f32 v13, v13, v14
	s_setprio 2
	v_cvt_pk_bf16_f32 v6, v130, v131
	v_cvt_pk_bf16_f32 v7, v132, v133
	v_cvt_pk_bf16_f32 v8, v135, v136
	v_cvt_pk_bf16_f32 v9, v137, v138
	v_cvt_pk_bf16_f32 v3, v141, v142
	v_cvt_pk_bf16_f32 v4, v143, v144
	v_cvt_pk_bf16_f32 v5, v145, v163
	v_subrev_u32_e32 v15, 64, v162
	v_cvt_f32_i32_e32 v96, v15
	s_add_i32 s57, s53, 0
	v_add_u32_e32 v14, s57, v0
	ds_read_b64_tr_b16 v[134:135], v14 offset:8192
	ds_read_b64_tr_b16 v[136:137], v14 offset:8704
	ds_read_b64_tr_b16 v[138:139], v14 offset:9216
	ds_read_b64_tr_b16 v[140:141], v14 offset:9728
	ds_read_b64_tr_b16 v[122:123], v14 offset:12288
	ds_read_b64_tr_b16 v[124:125], v14 offset:12800
	ds_read_b64_tr_b16 v[118:119], v14 offset:13312
	ds_read_b64_tr_b16 v[120:121], v14 offset:13824
	ds_read_b64_tr_b16 v[142:143], v14 offset:10240
	ds_read_b64_tr_b16 v[144:145], v14 offset:10752
	ds_read_b64_tr_b16 v[146:147], v14 offset:11264
	ds_read_b64_tr_b16 v[148:149], v14 offset:11776
	v_add_f32_e32 v97, 1.0, v96
	ds_read_b64_tr_b16 v[130:131], v14 offset:14336
	ds_read_b64_tr_b16 v[132:133], v14 offset:14848
	ds_read_b64_tr_b16 v[126:127], v14 offset:15360
	ds_read_b64_tr_b16 v[128:129], v14 offset:15872
	v_and_b32_e32 v14, 0x7fffffff, v96
	v_and_b32_e32 v15, 0x7fffffff, v97
	v_pk_fma_f32 v[14:15], v[154:155], v[14:15], v[80:81]
	v_cmp_le_f32_e64 vcc, |v97|, s77
	v_pk_add_f32 v[164:165], v[96:97], s[26:27] op_sel_hi:[1,0]
	s_waitcnt lgkmcnt(14)
	v_mfma_f32_32x32x16_bf16 v[32:47], v[134:137], v[114:117], v[32:47]
	v_cndmask_b32_e32 v80, v197, v15, vcc
	v_cmp_le_f32_e64 vcc, |v96|, s77
	v_and_b32_e32 v15, 0x7fffffff, v165
	v_add_f32_e64 v134, v96, s18
	v_add_f32_e64 v135, v96, s19
	v_cndmask_b32_e32 v81, v197, v14, vcc
	v_and_b32_e32 v14, 0x7fffffff, v164
	v_pk_fma_f32 v[64:65], v[154:155], v[14:15], v[64:65]
	v_cmp_le_f32_e64 vcc, |v165|, s77
	s_waitcnt lgkmcnt(10)
	v_mfma_f32_32x32x16_bf16 v[48:63], v[122:125], v[114:117], v[48:63]
	v_add_f32_e64 v136, v134, s26
	v_add_f32_e64 v137, v135, s26
	v_cndmask_b32_e32 v14, v197, v65, vcc
	v_cmp_le_f32_e64 vcc, |v164|, s77
	v_add_f32_e64 v164, v96, s8
	v_add_f32_e64 v165, v96, s9
	v_pk_add_f32 v[166:167], v[164:165], s[26:27] op_sel_hi:[1,0]
	v_cndmask_b32_e32 v15, v197, v64, vcc
	v_and_b32_e32 v65, 0x7fffffff, v167
	v_and_b32_e32 v64, 0x7fffffff, v166
	v_pk_fma_f32 v[66:67], v[154:155], v[64:65], v[66:67]
	v_cmp_le_f32_e64 vcc, |v167|, s77
	v_mfma_f32_32x32x16_bf16 v[32:47], v[138:141], v[10:13], v[32:47]
	s_nop 0
	v_cndmask_b32_e32 v64, v197, v67, vcc
	v_cmp_le_f32_e64 vcc, |v166|, s77
	v_and_b32_e32 v67, 0x7fffffff, v165
	s_nop 0
	v_cndmask_b32_e32 v65, v197, v66, vcc
	v_and_b32_e32 v66, 0x7fffffff, v164
	v_pk_fma_f32 v[82:83], v[154:155], v[66:67], v[82:83]
	v_cmp_le_f32_e64 vcc, |v165|, s77
	s_waitcnt lgkmcnt(8)
	v_mfma_f32_32x32x16_bf16 v[48:63], v[118:121], v[10:13], v[48:63]
	v_cndmask_b32_e32 v66, v197, v83, vcc
	v_cmp_le_f32_e64 vcc, |v164|, s77
	v_add_f32_e64 v164, v96, s10
	v_add_f32_e64 v165, v96, s11
	v_add_f32_e64 v166, v164, s26
	v_add_f32_e64 v167, v165, s26
	v_cndmask_b32_e32 v67, v197, v82, vcc
	v_and_b32_e32 v83, 0x7fffffff, v167
	v_and_b32_e32 v82, 0x7fffffff, v166
	v_pk_fma_f32 v[68:69], v[154:155], v[82:83], v[68:69]
	v_cmp_le_f32_e64 vcc, |v167|, s77
	s_waitcnt lgkmcnt(6)
	v_mfma_f32_32x32x16_bf16 v[32:47], v[142:145], v[6:9], v[32:47]
	v_cndmask_b32_e32 v82, v197, v69, vcc
	v_cmp_le_f32_e64 vcc, |v166|, s77
	v_and_b32_e32 v69, 0x7fffffff, v165
	s_nop 0
	v_cndmask_b32_e32 v83, v197, v68, vcc
	v_and_b32_e32 v68, 0x7fffffff, v164
	v_pk_fma_f32 v[84:85], v[154:155], v[68:69], v[84:85]
	v_cmp_le_f32_e64 vcc, |v165|, s77
	s_waitcnt lgkmcnt(2)
	v_mfma_f32_32x32x16_bf16 v[48:63], v[130:133], v[6:9], v[48:63]
	v_cndmask_b32_e32 v68, v197, v85, vcc
	v_cmp_le_f32_e64 vcc, |v164|, s77
	v_add_f32_e64 v164, v96, s12
	v_add_f32_e64 v165, v96, s13
	v_add_f32_e64 v166, v164, s26
	v_add_f32_e64 v167, v165, s26
	s_setprio 1
	v_cndmask_b32_e32 v69, v197, v84, vcc
	v_and_b32_e32 v85, 0x7fffffff, v167
	v_and_b32_e32 v84, 0x7fffffff, v166
	v_pk_fma_f32 v[70:71], v[154:155], v[84:85], v[70:71]
	v_cmp_le_f32_e64 vcc, |v167|, s77
	v_mfma_f32_32x32x16_bf16 v[32:47], v[146:149], v[2:5], v[32:47]
	s_nop 0
	v_cndmask_b32_e32 v84, v197, v71, vcc
	v_cmp_le_f32_e64 vcc, |v166|, s77
	v_and_b32_e32 v71, 0x7fffffff, v165
	s_nop 0
	v_cndmask_b32_e32 v85, v197, v70, vcc
	v_and_b32_e32 v70, 0x7fffffff, v164
	v_pk_fma_f32 v[86:87], v[154:155], v[70:71], v[86:87]
	v_cmp_le_f32_e64 vcc, |v165|, s77
	s_waitcnt lgkmcnt(0)
	v_mfma_f32_32x32x16_bf16 v[48:63], v[126:129], v[2:5], v[48:63]
	v_cndmask_b32_e32 v70, v197, v87, vcc
	v_cmp_le_f32_e64 vcc, |v164|, s77
	v_add_f32_e64 v164, v96, s14
	v_add_f32_e64 v165, v96, s15
	v_add_f32_e64 v166, v164, s26
	v_add_f32_e64 v167, v165, s26
	v_cndmask_b32_e32 v71, v197, v86, vcc
	v_and_b32_e32 v87, 0x7fffffff, v167
	v_and_b32_e32 v86, 0x7fffffff, v166
	v_pk_fma_f32 v[72:73], v[154:155], v[86:87], v[72:73]
	v_cmp_le_f32_e64 vcc, |v167|, s77
	s_nop 1
	v_cndmask_b32_e32 v86, v197, v73, vcc
	v_cmp_le_f32_e64 vcc, |v166|, s77
	v_and_b32_e32 v73, 0x7fffffff, v165
	s_nop 0
	v_cndmask_b32_e32 v87, v197, v72, vcc
	v_and_b32_e32 v72, 0x7fffffff, v164
	v_pk_fma_f32 v[88:89], v[154:155], v[72:73], v[88:89]
	v_cmp_le_f32_e64 vcc, |v165|, s77
	s_nop 1
	v_cndmask_b32_e32 v72, v197, v89, vcc
	v_cmp_le_f32_e64 vcc, |v164|, s77
	v_pk_add_f32 v[164:165], v[96:97], s[16:17] op_sel_hi:[0,1]
	v_pk_add_f32 v[166:167], v[164:165], s[26:27] op_sel_hi:[1,0]
	v_cndmask_b32_e32 v73, v197, v88, vcc
	v_and_b32_e32 v89, 0x7fffffff, v167
	v_and_b32_e32 v88, 0x7fffffff, v166
	v_pk_fma_f32 v[74:75], v[154:155], v[88:89], v[74:75]
	v_cmp_le_f32_e64 vcc, |v167|, s77
	v_pk_add_f32 v[96:97], v[96:97], s[20:21] op_sel_hi:[0,1]
	s_nop 0
	v_cndmask_b32_e32 v88, v197, v75, vcc
	v_cmp_le_f32_e64 vcc, |v166|, s77
	v_and_b32_e32 v75, 0x7fffffff, v165
	s_nop 0
	v_cndmask_b32_e32 v89, v197, v74, vcc
	v_and_b32_e32 v74, 0x7fffffff, v164
	v_pk_fma_f32 v[90:91], v[154:155], v[74:75], v[90:91]
	v_cmp_le_f32_e64 vcc, |v165|, s77
	s_nop 1
	v_cndmask_b32_e32 v74, v197, v91, vcc
	v_cmp_le_f32_e64 vcc, |v164|, s77
	v_and_b32_e32 v91, 0x7fffffff, v137
	s_nop 0
	v_cndmask_b32_e32 v75, v197, v90, vcc
	v_and_b32_e32 v90, 0x7fffffff, v136
	v_pk_fma_f32 v[76:77], v[154:155], v[90:91], v[76:77]
	v_cmp_le_f32_e64 vcc, |v137|, s77
	s_nop 1
	v_cndmask_b32_e32 v90, v197, v77, vcc
	v_cmp_le_f32_e64 vcc, |v136|, s77
	v_and_b32_e32 v77, 0x7fffffff, v135
	s_nop 0
	v_cndmask_b32_e32 v91, v197, v76, vcc
	v_and_b32_e32 v76, 0x7fffffff, v134
	v_pk_fma_f32 v[92:93], v[154:155], v[76:77], v[92:93]
	v_cmp_le_f32_e64 vcc, |v135|, s77
	s_nop 1
	v_cndmask_b32_e32 v76, v197, v93, vcc
	v_cmp_le_f32_e64 vcc, |v134|, s77
	v_pk_add_f32 v[134:135], v[96:97], s[26:27] op_sel_hi:[1,0]
	s_nop 0
	v_cndmask_b32_e32 v77, v197, v92, vcc
	v_and_b32_e32 v93, 0x7fffffff, v135
	v_and_b32_e32 v92, 0x7fffffff, v134
	v_pk_fma_f32 v[78:79], v[154:155], v[92:93], v[78:79]
	v_cmp_le_f32_e64 vcc, |v135|, s77
	s_nop 1
	v_cndmask_b32_e32 v92, v197, v79, vcc
	v_cmp_le_f32_e64 vcc, |v134|, s77
	v_and_b32_e32 v79, 0x7fffffff, v97
	s_nop 0
	v_cndmask_b32_e32 v93, v197, v78, vcc
	v_and_b32_e32 v78, 0x7fffffff, v96
	v_pk_fma_f32 v[94:95], v[154:155], v[78:79], v[94:95]
	v_cmp_le_f32_e64 vcc, |v97|, s77
	s_nop 1
	v_cndmask_b32_e32 v78, v197, v95, vcc
	v_max_f32_e32 v95, v80, v14
	v_cmp_le_f32_e64 vcc, |v96|, s77
	v_max3_f32 v96, v81, v15, v67
	v_max3_f32 v10, v95, v66, v64
	s_setprio 0
	v_max3_f32 v11, v96, v65, v69
	v_max3_f32 v10, v10, v68, v82
	v_max3_f32 v11, v11, v83, v71
	v_max3_f32 v10, v10, v70, v84
	v_max3_f32 v11, v11, v85, v73
	v_max3_f32 v10, v10, v72, v86
	v_max3_f32 v6, v11, v87, v75
	v_max3_f32 v7, v10, v74, v88
	v_cndmask_b32_e32 v79, v197, v94, vcc
	v_max3_f32 v6, v6, v89, v77
	v_max3_f32 v7, v7, v76, v90
	v_max3_f32 v6, v6, v91, v79
	v_max3_f32 v7, v7, v78, v92
	v_add_f32_e32 v94, v163, v168
	v_max3_f32 v2, v6, v93, v7
	v_add_f32_e32 v161, v161, v94
	v_cmp_lt_f32_e32 vcc, s33, v2
	s_cbranch_vccz .LBB0_385
	v_mov_b32_e32 v3, v2
	s_nop 1
	v_permlane32_swap_b32 v2, v3
	s_nop 1
	s_nop 0
	v_max3_f32 v3, v2, v3, 0
	v_exp_f32_e64 v2, -v3
	v_add_f32_e32 v151, v151, v3
	v_xor_b32_e32 v16, 0x80000000, v151
	v_sub_f32_e32 v81, v81, v3
	v_sub_f32_e32 v80, v80, v3
	v_sub_f32_e32 v67, v67, v3
	v_sub_f32_e32 v66, v66, v3
	v_sub_f32_e32 v69, v69, v3
	v_sub_f32_e32 v68, v68, v3
	v_sub_f32_e32 v71, v71, v3
	v_sub_f32_e32 v70, v70, v3
	v_sub_f32_e32 v73, v73, v3
	v_sub_f32_e32 v72, v72, v3
	v_sub_f32_e32 v75, v75, v3
	v_sub_f32_e32 v74, v74, v3
	v_sub_f32_e32 v77, v77, v3
	v_sub_f32_e32 v76, v76, v3
	v_sub_f32_e32 v79, v79, v3
	v_sub_f32_e32 v78, v78, v3
	v_sub_f32_e32 v15, v15, v3
	v_sub_f32_e32 v14, v14, v3
	v_sub_f32_e32 v65, v65, v3
	v_sub_f32_e32 v64, v64, v3
	v_sub_f32_e32 v83, v83, v3
	v_sub_f32_e32 v82, v82, v3
	v_sub_f32_e32 v85, v85, v3
	v_sub_f32_e32 v84, v84, v3
	v_sub_f32_e32 v87, v87, v3
	v_sub_f32_e32 v86, v86, v3
	v_sub_f32_e32 v89, v89, v3
	v_sub_f32_e32 v88, v88, v3
	v_sub_f32_e32 v91, v91, v3
	v_sub_f32_e32 v90, v90, v3
	v_sub_f32_e32 v93, v93, v3
	v_sub_f32_e32 v92, v92, v3
	v_mov_b32_e32 v17, v16
	v_mov_b32_e32 v18, v16
	v_mov_b32_e32 v19, v16
	v_mov_b32_e32 v20, v16
	v_mov_b32_e32 v21, v16
	v_mov_b32_e32 v22, v16
	v_mov_b32_e32 v23, v16
	v_mov_b32_e32 v24, v16
	v_mov_b32_e32 v25, v16
	v_mov_b32_e32 v26, v16
	v_mov_b32_e32 v27, v16
	v_mov_b32_e32 v28, v16
	v_mov_b32_e32 v29, v16
	v_mov_b32_e32 v30, v16
	v_mov_b32_e32 v31, v16
	v_pk_mul_f32 v[46:47], v[46:47], v[2:3] op_sel_hi:[1,0]
	v_pk_mul_f32 v[44:45], v[44:45], v[2:3] op_sel_hi:[1,0]
	v_pk_mul_f32 v[42:43], v[42:43], v[2:3] op_sel_hi:[1,0]
	v_pk_mul_f32 v[40:41], v[40:41], v[2:3] op_sel_hi:[1,0]
	v_pk_mul_f32 v[38:39], v[38:39], v[2:3] op_sel_hi:[1,0]
	v_pk_mul_f32 v[36:37], v[36:37], v[2:3] op_sel_hi:[1,0]
	v_pk_mul_f32 v[34:35], v[34:35], v[2:3] op_sel_hi:[1,0]
	v_pk_mul_f32 v[32:33], v[32:33], v[2:3] op_sel_hi:[1,0]
	v_pk_mul_f32 v[62:63], v[62:63], v[2:3] op_sel_hi:[1,0]
	v_pk_mul_f32 v[60:61], v[60:61], v[2:3] op_sel_hi:[1,0]
	v_pk_mul_f32 v[58:59], v[58:59], v[2:3] op_sel_hi:[1,0]
	v_pk_mul_f32 v[56:57], v[56:57], v[2:3] op_sel_hi:[1,0]
	v_pk_mul_f32 v[54:55], v[54:55], v[2:3] op_sel_hi:[1,0]
	v_pk_mul_f32 v[52:53], v[52:53], v[2:3] op_sel_hi:[1,0]
	v_pk_mul_f32 v[50:51], v[50:51], v[2:3] op_sel_hi:[1,0]
	v_pk_mul_f32 v[48:49], v[48:49], v[2:3] op_sel_hi:[1,0]
	v_mul_f32_e32 v161, v161, v2
.LBB0_385:
	s_waitcnt vmcnt(0)
	s_cmp_ge_i32 s29, s54
	s_barrier
	s_setprio 3
	s_cbranch_scc1 .LBB0_387
	s_add_i32 s56, s56, -2
	s_ashr_i32 s58, s56, 2
	s_ashr_i32 s59, s58, 31
	s_and_b32 s56, s56, 3
	s_lshl_b64 s[58:59], s[58:59], 21
	v_lshl_add_u64 v[2:3], v[152:153], 0, s[58:59]
	s_mul_i32 s78, s56, 0x38000
	s_add_i32 s56, s57, s27
	v_lshl_add_u64 v[2:3], v[2:3], 0, s[78:79]
	s_mov_b32 m0, s56
	s_nop 0
	global_load_lds_dwordx4 v[2:3], off
	v_lshl_add_u64 v[2:3], v[156:157], 0, s[58:59]
	v_lshl_add_u64 v[2:3], v[2:3], 0, s[78:79]
	s_add_i32 m0, s56, 0x2000
	s_nop 0
	global_load_lds_dwordx4 v[2:3], off
.LBB0_387:
	v_exp_f32_e32 v122, v81
	v_exp_f32_e32 v123, v80
	v_exp_f32_e32 v124, v67
	v_exp_f32_e32 v125, v66
	v_exp_f32_e32 v126, v69
	v_exp_f32_e32 v127, v68
	v_exp_f32_e32 v128, v71
	v_exp_f32_e32 v129, v70
	v_exp_f32_e32 v130, v73
	v_exp_f32_e32 v131, v72
	v_exp_f32_e32 v132, v75
	v_exp_f32_e32 v133, v74
	v_exp_f32_e32 v134, v77
	v_exp_f32_e32 v135, v76
	v_exp_f32_e32 v136, v79
	v_exp_f32_e32 v137, v78
	v_add_u32_e32 v94, s3, v159
	ds_read_b128 v[2:5], v94
	ds_read_b128 v[6:9], v94 offset:512
	v_exp_f32_e32 v138, v87
	v_exp_f32_e32 v139, v86
	v_exp_f32_e32 v140, v89
	s_waitcnt lgkmcnt(0)
	v_mfma_f32_32x32x16_bf16 v[66:81], v[2:5], v[110:113], v[16:31]
	ds_read_b128 v[2:5], v94 offset:2048
	ds_read_b128 v[10:13], v94 offset:2560
	v_exp_f32_e32 v141, v88
	v_exp_f32_e32 v142, v91
	v_exp_f32_e32 v143, v90
	v_exp_f32_e32 v144, v93
	v_exp_f32_e32 v165, v92
	s_waitcnt lgkmcnt(0)
	v_mfma_f32_32x32x16_bf16 v[66:81], v[2:5], v[106:109], v[66:81]
	ds_read_b128 v[2:5], v94 offset:4096
	ds_read_b128 v[114:117], v94 offset:4608
	s_waitcnt lgkmcnt(0)
	v_mfma_f32_32x32x16_bf16 v[66:81], v[2:5], v[102:105], v[66:81]
	ds_read_b128 v[2:5], v94 offset:6144
	ds_read_b128 v[118:121], v94 offset:6656
	s_waitcnt lgkmcnt(0)
	v_mfma_f32_32x32x16_bf16 v[66:81], v[2:5], v[98:101], v[66:81]
	v_exp_f32_e32 v2, v15
	v_exp_f32_e32 v3, v14
	v_exp_f32_e32 v4, v65
	v_exp_f32_e32 v5, v64
	v_exp_f32_e32 v14, v83
	v_exp_f32_e32 v15, v82
	v_exp_f32_e32 v64, v85
	v_exp_f32_e32 v65, v84
	v_mfma_f32_32x32x16_bf16 v[82:97], v[6:9], v[110:113], v[16:31]
	v_add_f32_e32 v6, v122, v123
	v_add_f32_e32 v6, v124, v6
	v_add_f32_e32 v6, v125, v6
	v_add_f32_e32 v6, v126, v6
	v_add_f32_e32 v6, v127, v6
	v_add_f32_e32 v6, v128, v6
	v_add_f32_e32 v6, v129, v6
	v_mfma_f32_32x32x16_bf16 v[82:97], v[10:13], v[106:109], v[82:97]
	v_add_f32_e32 v6, v130, v6
	v_add_f32_e32 v6, v131, v6
	v_add_f32_e32 v6, v132, v6
	v_add_f32_e32 v6, v133, v6
	v_add_f32_e32 v6, v134, v6
	v_add_f32_e32 v6, v135, v6
	v_add_f32_e32 v6, v136, v6
	v_mfma_f32_32x32x16_bf16 v[82:97], v[114:117], v[102:105], v[82:97]
	v_add_f32_e32 v6, v137, v6
	v_add_f32_e32 v6, v2, v6
	v_add_f32_e32 v6, v3, v6
	v_add_f32_e32 v6, v4, v6
	v_add_f32_e32 v6, v5, v6
	v_add_f32_e32 v6, v14, v6
	v_add_f32_e32 v6, v15, v6
	v_add_f32_e32 v6, v64, v6
	v_add_f32_e32 v6, v65, v6
	v_mfma_f32_32x32x16_bf16 v[82:97], v[118:121], v[98:101], v[82:97]
	v_add_f32_e32 v6, v138, v6
	v_add_f32_e32 v6, v139, v6
	v_add_f32_e32 v6, v140, v6
	v_add_f32_e32 v6, v141, v6
	v_add_f32_e32 v6, v142, v6
	v_add_f32_e32 v6, v143, v6
	v_add_f32_e32 v168, v144, v6
	v_cvt_pk_bf16_f32 v6, v2, v3
	s_setprio 2
	v_cvt_pk_bf16_f32 v2, v138, v139
	v_cvt_pk_bf16_f32 v122, v122, v123
	v_cvt_pk_bf16_f32 v123, v124, v125
	v_cvt_pk_bf16_f32 v124, v126, v127
	v_cvt_pk_bf16_f32 v125, v128, v129
	v_cvt_pk_bf16_f32 v114, v130, v131
	v_cvt_pk_bf16_f32 v115, v132, v133
	v_cvt_pk_bf16_f32 v116, v134, v135
	v_cvt_pk_bf16_f32 v117, v136, v137
	v_cvt_pk_bf16_f32 v7, v4, v5
	v_cvt_pk_bf16_f32 v8, v14, v15
	v_cvt_pk_bf16_f32 v9, v64, v65
	v_cvt_pk_bf16_f32 v3, v140, v141
	v_cvt_pk_bf16_f32 v4, v142, v143
	v_cvt_pk_bf16_f32 v5, v144, v165
	v_cvt_f32_i32_e32 v14, v162
	v_add_u32_e32 v12, s2, v0
	ds_read_b64_tr_b16 v[146:147], v12 offset:8192
	ds_read_b64_tr_b16 v[148:149], v12 offset:8704
	ds_read_b64_tr_b16 v[130:131], v12 offset:12288
	ds_read_b64_tr_b16 v[132:133], v12 offset:12800
	ds_read_b64_tr_b16 v[138:139], v12 offset:9216
	ds_read_b64_tr_b16 v[140:141], v12 offset:9728
	ds_read_b64_tr_b16 v[126:127], v12 offset:13312
	ds_read_b64_tr_b16 v[128:129], v12 offset:13824
	ds_read_b64_tr_b16 v[134:135], v12 offset:10240
	ds_read_b64_tr_b16 v[136:137], v12 offset:10752
	ds_read_b64_tr_b16 v[118:119], v12 offset:14336
	ds_read_b64_tr_b16 v[120:121], v12 offset:14848
	ds_read_b64_tr_b16 v[142:143], v12 offset:11264
	ds_read_b64_tr_b16 v[144:145], v12 offset:11776
	ds_read_b64_tr_b16 v[10:11], v12 offset:15360
	ds_read_b64_tr_b16 v[12:13], v12 offset:15872
	s_waitcnt lgkmcnt(14)
	v_mfma_f32_32x32x16_bf16 v[32:47], v[146:149], v[122:125], v[32:47]
	v_add_f32_e32 v15, 1.0, v14
	v_and_b32_e32 v64, 0x7fffffff, v14
	v_and_b32_e32 v65, 0x7fffffff, v15
	v_fma_f32 v64, v154, v64, v66
	v_fma_f32 v65, v155, v65, v67
	v_cmp_le_f32_e64 vcc, |v14|, s77
	v_cmp_le_f32_e64 s[2:3], |v15|, s77
	s_mov_b32 s78, s76
	v_cndmask_b32_e32 v164, v197, v64, vcc
	v_cndmask_b32_e64 v163, v197, v65, s[2:3]
	v_pk_add_f32 v[64:65], v[14:15], s[26:27] op_sel_hi:[1,0]
	s_waitcnt lgkmcnt(12)
	v_mfma_f32_32x32x16_bf16 v[48:63], v[130:133], v[122:125], v[48:63]
	v_and_b32_e32 v67, 0x7fffffff, v65
	v_and_b32_e32 v66, 0x7fffffff, v64
	v_fma_f32 v66, v154, v66, v82
	v_fma_f32 v67, v155, v67, v83
	v_cmp_le_f32_e64 vcc, |v64|, s77
	v_cmp_le_f32_e64 s[2:3], |v65|, s77
	v_pk_add_f32 v[82:83], v[14:15], s[8:9] op_sel_hi:[0,1]
	v_cndmask_b32_e32 v64, v197, v66, vcc
	v_cndmask_b32_e64 v65, v197, v67, s[2:3]
	v_pk_add_f32 v[66:67], v[82:83], s[26:27] op_sel_hi:[1,0]
	s_waitcnt lgkmcnt(10)
	v_mfma_f32_32x32x16_bf16 v[32:47], v[138:141], v[114:117], v[32:47]
	v_and_b32_e32 v167, 0x7fffffff, v67
	v_and_b32_e32 v166, 0x7fffffff, v66
	v_fma_f32 v84, v154, v166, v84
	v_fma_f32 v85, v155, v167, v85
	v_cmp_le_f32_e64 vcc, |v66|, s77
	v_cmp_le_f32_e64 s[2:3], |v67|, s77
	s_nop 0
	v_cndmask_b32_e32 v66, v197, v84, vcc
	v_cndmask_b32_e64 v67, v197, v85, s[2:3]
	v_and_b32_e32 v85, 0x7fffffff, v83
	v_and_b32_e32 v84, 0x7fffffff, v82
	v_pk_fma_f32 v[68:69], v[154:155], v[84:85], v[68:69]
	v_cmp_le_f32_e64 s[2:3], |v83|, s77
	v_cmp_le_f32_e64 vcc, |v82|, s77
	s_waitcnt lgkmcnt(8)
	v_mfma_f32_32x32x16_bf16 v[48:63], v[126:129], v[114:117], v[48:63]
	v_cndmask_b32_e64 v15, v197, v69, s[2:3]
	v_add_f32_e64 v84, v14, s10
	v_add_f32_e64 v85, v14, s11
	v_cndmask_b32_e32 v82, v197, v68, vcc
	v_add_f32_e64 v68, v84, s26
	v_add_f32_e64 v69, v85, s26
	v_and_b32_e32 v167, 0x7fffffff, v69
	v_and_b32_e32 v166, 0x7fffffff, v68
	v_pk_fma_f32 v[86:87], v[154:155], v[166:167], v[86:87]
	v_cmp_le_f32_e64 vcc, |v68|, s77
	v_cmp_le_f32_e64 s[2:3], |v69|, s77
	s_waitcnt lgkmcnt(6)
	v_mfma_f32_32x32x16_bf16 v[32:47], v[134:137], v[6:9], v[32:47]
	v_cndmask_b32_e32 v68, v197, v86, vcc
	v_cndmask_b32_e64 v69, v197, v87, s[2:3]
	v_and_b32_e32 v87, 0x7fffffff, v85
	v_and_b32_e32 v86, 0x7fffffff, v84
	v_fma_f32 v70, v154, v86, v70
	v_fma_f32 v71, v155, v87, v71
	v_cmp_le_f32_e64 vcc, |v84|, s77
	v_cmp_le_f32_e64 s[2:3], |v85|, s77
	v_pk_add_f32 v[86:87], v[14:15], s[12:13] op_sel_hi:[0,1]
	v_cndmask_b32_e32 v84, v197, v70, vcc
	v_cndmask_b32_e64 v83, v197, v71, s[2:3]
	v_pk_add_f32 v[70:71], v[86:87], s[26:27] op_sel_hi:[1,0]
	s_waitcnt lgkmcnt(4)
	v_mfma_f32_32x32x16_bf16 v[48:63], v[118:121], v[6:9], v[48:63]
	v_and_b32_e32 v167, 0x7fffffff, v71
	s_setprio 1
	v_and_b32_e32 v166, 0x7fffffff, v70
	v_fma_f32 v88, v154, v166, v88
	v_fma_f32 v89, v155, v167, v89
	v_cmp_le_f32_e64 vcc, |v70|, s77
	v_cmp_le_f32_e64 s[2:3], |v71|, s77
	s_nop 0
	v_cndmask_b32_e32 v70, v197, v88, vcc
	v_cndmask_b32_e64 v71, v197, v89, s[2:3]
	v_and_b32_e32 v89, 0x7fffffff, v87
	v_and_b32_e32 v88, 0x7fffffff, v86
	v_pk_fma_f32 v[72:73], v[154:155], v[88:89], v[72:73]
	v_cmp_le_f32_e64 vcc, |v86|, s77
	v_cmp_le_f32_e64 s[2:3], |v87|, s77
	v_pk_add_f32 v[88:89], v[14:15], s[14:15] op_sel_hi:[0,1]
	v_cndmask_b32_e32 v86, v197, v72, vcc
	v_cndmask_b32_e64 v85, v197, v73, s[2:3]
	v_pk_add_f32 v[72:73], v[88:89], s[26:27] op_sel_hi:[1,0]
	s_waitcnt lgkmcnt(2)
	v_mfma_f32_32x32x16_bf16 v[32:47], v[142:145], v[2:5], v[32:47]
	v_and_b32_e32 v167, 0x7fffffff, v73
	v_and_b32_e32 v166, 0x7fffffff, v72
	v_fma_f32 v90, v154, v166, v90
	v_fma_f32 v91, v155, v167, v91
	v_cmp_le_f32_e64 vcc, |v72|, s77
	v_cmp_le_f32_e64 s[2:3], |v73|, s77
	s_nop 0
	v_cndmask_b32_e32 v72, v197, v90, vcc
	v_cndmask_b32_e64 v73, v197, v91, s[2:3]
	v_and_b32_e32 v91, 0x7fffffff, v89
	v_and_b32_e32 v90, 0x7fffffff, v88
	v_pk_fma_f32 v[74:75], v[154:155], v[90:91], v[74:75]
	v_cmp_le_f32_e64 vcc, |v88|, s77
	v_cmp_le_f32_e64 s[2:3], |v89|, s77
	v_pk_add_f32 v[90:91], v[14:15], s[16:17] op_sel_hi:[0,1]
	v_cndmask_b32_e32 v88, v197, v74, vcc
	v_cndmask_b32_e64 v87, v197, v75, s[2:3]
	v_pk_add_f32 v[74:75], v[90:91], s[26:27] op_sel_hi:[1,0]
	s_waitcnt lgkmcnt(0)
	v_mfma_f32_32x32x16_bf16 v[48:63], v[10:13], v[2:5], v[48:63]
	v_and_b32_e32 v167, 0x7fffffff, v75
	v_and_b32_e32 v166, 0x7fffffff, v74
	v_fma_f32 v92, v154, v166, v92
	v_fma_f32 v93, v155, v167, v93
	v_cmp_le_f32_e64 vcc, |v74|, s77
	v_cmp_le_f32_e64 s[2:3], |v75|, s77
	s_nop 0
	v_cndmask_b32_e32 v74, v197, v92, vcc
	v_cndmask_b32_e64 v75, v197, v93, s[2:3]
	v_and_b32_e32 v93, 0x7fffffff, v91
	v_and_b32_e32 v92, 0x7fffffff, v90
	v_pk_fma_f32 v[76:77], v[154:155], v[92:93], v[76:77]
	v_cmp_le_f32_e64 vcc, |v90|, s77
	v_cmp_le_f32_e64 s[2:3], |v91|, s77
	v_pk_add_f32 v[92:93], v[14:15], s[18:19] op_sel_hi:[0,1]
	v_cndmask_b32_e32 v90, v197, v76, vcc
	v_cndmask_b32_e64 v89, v197, v77, s[2:3]
	v_pk_add_f32 v[76:77], v[92:93], s[26:27] op_sel_hi:[1,0]
	s_nop 0
	v_and_b32_e32 v167, 0x7fffffff, v77
	v_and_b32_e32 v166, 0x7fffffff, v76
	v_pk_fma_f32 v[94:95], v[154:155], v[166:167], v[94:95]
	v_cmp_le_f32_e64 vcc, |v76|, s77
	v_cmp_le_f32_e64 s[2:3], |v77|, s77
	s_nop 0
	v_cndmask_b32_e32 v76, v197, v94, vcc
	v_cndmask_b32_e64 v77, v197, v95, s[2:3]
	v_and_b32_e32 v95, 0x7fffffff, v93
	v_and_b32_e32 v94, 0x7fffffff, v92
	v_pk_fma_f32 v[78:79], v[154:155], v[94:95], v[78:79]
	v_cmp_le_f32_e64 vcc, |v92|, s77
	v_cmp_le_f32_e64 s[2:3], |v93|, s77
	v_pk_add_f32 v[94:95], v[14:15], s[20:21] op_sel_hi:[0,1]
	v_cndmask_b32_e32 v92, v197, v78, vcc
	v_cndmask_b32_e64 v91, v197, v79, s[2:3]
	v_pk_add_f32 v[78:79], v[94:95], s[26:27] op_sel_hi:[1,0]
	v_max_f32_e32 v93, v163, v65
	v_and_b32_e32 v167, 0x7fffffff, v79
	v_and_b32_e32 v166, 0x7fffffff, v78
	v_pk_fma_f32 v[96:97], v[154:155], v[166:167], v[96:97]
	v_cmp_le_f32_e64 vcc, |v78|, s77
	v_max3_f32 v93, v93, v15, v67
	v_max3_f32 v93, v93, v83, v69
	v_cndmask_b32_e32 v78, v197, v96, vcc
	v_and_b32_e32 v96, 0x7fffffff, v94
	v_cmp_le_f32_e64 vcc, |v94|, s77
	v_max3_f32 v94, v164, v64, v82
	v_max3_f32 v94, v94, v66, v84
	v_cmp_le_f32_e64 s[2:3], |v79|, s77
	v_max3_f32 v94, v94, v68, v86
	v_max3_f32 v93, v93, v85, v71
	v_cndmask_b32_e64 v79, v197, v97, s[2:3]
	v_and_b32_e32 v97, 0x7fffffff, v95
	v_max3_f32 v94, v94, v70, v88
	v_max3_f32 v93, v93, v87, v73
	v_pk_fma_f32 v[80:81], v[154:155], v[96:97], v[80:81]
	v_cmp_le_f32_e64 s[2:3], |v95|, s77
	v_max3_f32 v94, v94, v72, v90
	v_max3_f32 v93, v93, v89, v75
	v_cndmask_b32_e64 v14, v197, v81, s[2:3]
	v_cndmask_b32_e32 v80, v197, v80, vcc
	v_max3_f32 v94, v94, v74, v92
	v_max3_f32 v93, v93, v91, v77
	v_max3_f32 v94, v94, v76, v80
	v_max3_f32 v93, v93, v14, v79
	v_add_f32_e32 v81, v165, v168
	s_setprio 0
	v_max3_f32 v2, v94, v78, v93
	v_add_f32_e32 v161, v161, v81
	v_cmp_lt_f32_e32 vcc, s33, v2
	s_cbranch_vccz .LBB0_389
	v_mov_b32_e32 v3, v2
	s_nop 1
	v_permlane32_swap_b32 v2, v3
	s_nop 1
	s_nop 0
	v_max3_f32 v3, v2, v3, 0
	v_exp_f32_e64 v2, -v3
	v_add_f32_e32 v151, v151, v3
	v_xor_b32_e32 v16, 0x80000000, v151
	v_sub_f32_e32 v164, v164, v3
	v_pk_mul_f32 v[46:47], v[46:47], v[2:3] op_sel_hi:[1,0]
	v_pk_mul_f32 v[44:45], v[44:45], v[2:3] op_sel_hi:[1,0]
	v_pk_mul_f32 v[42:43], v[42:43], v[2:3] op_sel_hi:[1,0]
	v_pk_mul_f32 v[40:41], v[40:41], v[2:3] op_sel_hi:[1,0]
	v_pk_mul_f32 v[38:39], v[38:39], v[2:3] op_sel_hi:[1,0]
	v_pk_mul_f32 v[36:37], v[36:37], v[2:3] op_sel_hi:[1,0]
	v_pk_mul_f32 v[34:35], v[34:35], v[2:3] op_sel_hi:[1,0]
	v_pk_mul_f32 v[32:33], v[32:33], v[2:3] op_sel_hi:[1,0]
	v_pk_mul_f32 v[62:63], v[62:63], v[2:3] op_sel_hi:[1,0]
	v_pk_mul_f32 v[60:61], v[60:61], v[2:3] op_sel_hi:[1,0]
	v_pk_mul_f32 v[58:59], v[58:59], v[2:3] op_sel_hi:[1,0]
	v_pk_mul_f32 v[56:57], v[56:57], v[2:3] op_sel_hi:[1,0]
	v_pk_mul_f32 v[54:55], v[54:55], v[2:3] op_sel_hi:[1,0]
	v_pk_mul_f32 v[52:53], v[52:53], v[2:3] op_sel_hi:[1,0]
	v_pk_mul_f32 v[50:51], v[50:51], v[2:3] op_sel_hi:[1,0]
	v_pk_mul_f32 v[48:49], v[48:49], v[2:3] op_sel_hi:[1,0]
	v_mul_f32_e32 v161, v161, v2
	v_sub_f32_e32 v163, v163, v3
	v_sub_f32_e32 v82, v82, v3
	v_sub_f32_e32 v15, v15, v3
	v_sub_f32_e32 v84, v84, v3
	v_sub_f32_e32 v83, v83, v3
	v_sub_f32_e32 v86, v86, v3
	v_sub_f32_e32 v85, v85, v3
	v_sub_f32_e32 v88, v88, v3
	v_sub_f32_e32 v87, v87, v3
	v_sub_f32_e32 v90, v90, v3
	v_sub_f32_e32 v89, v89, v3
	v_sub_f32_e32 v92, v92, v3
	v_sub_f32_e32 v91, v91, v3
	v_sub_f32_e32 v80, v80, v3
	v_sub_f32_e32 v14, v14, v3
	v_sub_f32_e32 v79, v79, v3
	v_sub_f32_e32 v78, v78, v3
	v_sub_f32_e32 v77, v77, v3
	v_sub_f32_e32 v76, v76, v3
	v_sub_f32_e32 v75, v75, v3
	v_sub_f32_e32 v74, v74, v3
	v_sub_f32_e32 v73, v73, v3
	v_sub_f32_e32 v72, v72, v3
	v_sub_f32_e32 v71, v71, v3
	v_sub_f32_e32 v70, v70, v3
	v_sub_f32_e32 v69, v69, v3
	v_sub_f32_e32 v68, v68, v3
	v_sub_f32_e32 v67, v67, v3
	v_sub_f32_e32 v66, v66, v3
	v_sub_f32_e32 v65, v65, v3
	v_sub_f32_e32 v64, v64, v3
	v_mov_b32_e32 v17, v16
	v_mov_b32_e32 v18, v16
	v_mov_b32_e32 v19, v16
	v_mov_b32_e32 v20, v16
	v_mov_b32_e32 v21, v16
	v_mov_b32_e32 v22, v16
	v_mov_b32_e32 v23, v16
	v_mov_b32_e32 v24, v16
	v_mov_b32_e32 v25, v16
	v_mov_b32_e32 v26, v16
	v_mov_b32_e32 v27, v16
	v_mov_b32_e32 v28, v16
	v_mov_b32_e32 v29, v16
	v_mov_b32_e32 v30, v16
	v_mov_b32_e32 v31, v16

.LBB0_399:
	s_setprio 3
	s_add_i32 s34, s56, 0xfffc0000
	s_add_i32 s30, s55, -1
	s_and_b32 s34, s34, 0xf00000
	s_and_b32 s30, s30, 3
	s_lshl_b32 s78, s34, 1
	s_add_i32 s54, s29, 0
	v_lshl_add_u64 v[34:35], v[116:117], 0, s[78:79]
	s_mul_i32 s58, s30, 0x38000
	s_mov_b32 s59, s79
	s_add_i32 s34, s54, s5
	v_lshl_add_u64 v[34:35], v[34:35], 0, s[58:59]
	s_mov_b32 m0, s34
	s_add_i32 s35, s34, 0x2000
	global_load_lds_dwordx4 v[34:35], off
	v_lshl_add_u64 v[34:35], v[118:119], 0, s[78:79]
	v_lshl_add_u64 v[34:35], v[34:35], 0, s[58:59]
	s_mov_b32 m0, s35
	s_mov_b32 s30, s27
	global_load_lds_dwordx4 v[34:35], off
	s_mov_b32 s27, s72
	s_add_i32 s53, s30, 0
	v_add_u32_e32 v0, s53, v126
	ds_read_b128 v[34:37], v0
	ds_read_b128 v[38:41], v0 offset:2048
	v_exp_f32_e32 v145, v66
	v_exp_f32_e32 v146, v67
	v_exp_f32_e32 v147, v68
	v_exp_f32_e32 v148, v69
	v_exp_f32_e32 v149, v70
	v_exp_f32_e32 v150, v71
	v_exp_f32_e32 v151, v72
	s_waitcnt lgkmcnt(0)
	v_mfma_f32_32x32x16_bf16 v[82:97], v[34:37], v[110:113], v[50:65]
	ds_read_b128 v[34:37], v0 offset:4096
	v_exp_f32_e32 v152, v73
	v_exp_f32_e32 v153, v74
	v_exp_f32_e32 v154, v75
	v_exp_f32_e32 v155, v76
	v_exp_f32_e32 v156, v77
	v_exp_f32_e32 v157, v78
	v_mfma_f32_32x32x16_bf16 v[82:97], v[38:41], v[106:109], v[82:97]
	ds_read_b128 v[38:41], v0 offset:6144
	v_exp_f32_e32 v158, v79
	v_exp_f32_e32 v159, v80
	v_exp_f32_e32 v160, v81
	s_waitcnt lgkmcnt(0)
	v_mfma_f32_32x32x16_bf16 v[82:97], v[34:37], v[102:105], v[82:97]
	v_add_f32_e32 v34, v129, v131
	v_add_f32_e32 v66, v132, v34
	ds_read_b128 v[34:37], v0 offset:512
	ds_read_b128 v[42:45], v0 offset:2560
	ds_read_b128 v[46:49], v0 offset:4608
	v_mfma_f32_32x32x16_bf16 v[82:97], v[38:41], v[98:101], v[82:97]
	ds_read_b128 v[38:41], v0 offset:6656
	v_add_f32_e32 v0, v135, v66
	v_add_f32_e32 v0, v136, v0
	v_add_f32_e32 v0, v139, v0
	v_add_f32_e32 v0, v140, v0
	v_add_f32_e32 v0, v143, v0
	v_add_f32_e32 v0, v130, v0
	s_waitcnt lgkmcnt(0)
	v_mfma_f32_32x32x16_bf16 v[66:81], v[34:37], v[110:113], v[50:65]
	v_add_f32_e32 v0, v133, v0
	v_add_f32_e32 v0, v134, v0
	v_add_f32_e32 v0, v137, v0
	v_add_f32_e32 v0, v138, v0
	s_setprio 2
	v_add_f32_e32 v0, v141, v0
	v_add_f32_e32 v0, v142, v0
	v_add_f32_e32 v0, v144, v0
	v_mfma_f32_32x32x16_bf16 v[66:81], v[42:45], v[106:109], v[66:81]
	v_add_f32_e32 v0, v145, v0
	v_add_f32_e32 v0, v146, v0
	v_add_f32_e32 v0, v147, v0
	v_add_f32_e32 v0, v148, v0
	v_add_f32_e32 v0, v149, v0
	v_add_f32_e32 v0, v150, v0
	v_add_f32_e32 v0, v151, v0
	v_mfma_f32_32x32x16_bf16 v[66:81], v[46:49], v[102:105], v[66:81]
	v_add_f32_e32 v0, v152, v0
	v_add_f32_e32 v0, v153, v0
	v_add_f32_e32 v0, v154, v0
	v_add_f32_e32 v0, v155, v0
	v_add_f32_e32 v0, v156, v0
	v_add_f32_e32 v0, v157, v0
	v_add_f32_e32 v0, v158, v0
	v_mfma_f32_32x32x16_bf16 v[66:81], v[38:41], v[98:101], v[66:81]
	v_cvt_pk_bf16_f32 v34, v129, v131
	v_add_f32_e32 v161, v159, v0
	v_cvt_pk_bf16_f32 v35, v132, v135
	v_cvt_pk_bf16_f32 v36, v136, v139
	v_cvt_pk_bf16_f32 v37, v140, v143
	v_cvt_pk_bf16_f32 v38, v130, v133
	v_cvt_pk_bf16_f32 v39, v134, v137
	v_cvt_pk_bf16_f32 v40, v138, v141
	v_cvt_pk_bf16_f32 v41, v142, v144
	v_cvt_pk_bf16_f32 v42, v145, v146
	v_cvt_pk_bf16_f32 v43, v147, v148
	v_cvt_pk_bf16_f32 v44, v149, v150
	v_cvt_pk_bf16_f32 v45, v151, v152
	v_cvt_pk_bf16_f32 v46, v153, v154
	v_cvt_pk_bf16_f32 v47, v155, v156
	v_cvt_pk_bf16_f32 v48, v157, v158
	v_cvt_pk_bf16_f32 v49, v159, v160
	s_add_i32 s57, s72, 0
	v_add_u32_e32 v0, s57, v125
	ds_read_b64_tr_b16 v[130:131], v0 offset:8192
	ds_read_b64_tr_b16 v[132:133], v0 offset:8704
	ds_read_b64_tr_b16 v[134:135], v0 offset:12288
	v_max_f32_e32 v129, v67, v67
	s_waitcnt lgkmcnt(1)
	v_mfma_f32_32x32x16_bf16 v[18:33], v[130:133], v[34:37], v[18:33]
	ds_read_b64_tr_b16 v[136:137], v0 offset:12800
	ds_read_b64_tr_b16 v[130:131], v0 offset:9216
	s_waitcnt lgkmcnt(1)
	v_mfma_f32_32x32x16_bf16 v[2:17], v[134:137], v[34:37], v[2:17]
	ds_read_b64_tr_b16 v[132:133], v0 offset:9728
	ds_read_b64_tr_b16 v[34:35], v0 offset:13312
	s_waitcnt lgkmcnt(1)
	v_mfma_f32_32x32x16_bf16 v[18:33], v[130:133], v[38:41], v[18:33]
	ds_read_b64_tr_b16 v[36:37], v0 offset:13824
	ds_read_b64_tr_b16 v[130:131], v0 offset:10240
	s_waitcnt lgkmcnt(1)
	v_mfma_f32_32x32x16_bf16 v[2:17], v[34:37], v[38:41], v[2:17]
	ds_read_b64_tr_b16 v[132:133], v0 offset:10752
	ds_read_b64_tr_b16 v[34:35], v0 offset:11264
	ds_read_b64_tr_b16 v[36:37], v0 offset:11776
	ds_read_b64_tr_b16 v[38:39], v0 offset:14336
	ds_read_b64_tr_b16 v[40:41], v0 offset:14848
	ds_read_b64_tr_b16 v[134:135], v0 offset:15360
	ds_read_b64_tr_b16 v[136:137], v0 offset:15872
	s_waitcnt lgkmcnt(6)
	v_mfma_f32_32x32x16_bf16 v[18:33], v[130:133], v[42:45], v[18:33]
	v_max_f32_e32 v130, v83, v83
	v_max_f32_e32 v129, v130, v129
	v_max3_f32 v130, v82, v66, v84
	s_setprio 1
	v_max3_f32 v129, v129, v85, v69
	v_max3_f32 v130, v130, v68, v86
	v_max3_f32 v129, v129, v87, v71
	s_waitcnt lgkmcnt(2)
	v_mfma_f32_32x32x16_bf16 v[2:17], v[38:41], v[42:45], v[2:17]
	v_max3_f32 v38, v130, v70, v88
	v_max3_f32 v39, v129, v89, v73
	v_max3_f32 v38, v38, v72, v90
	v_max3_f32 v39, v39, v91, v75
	v_max3_f32 v38, v38, v74, v92
	v_max3_f32 v39, v39, v93, v77
	v_max3_f32 v38, v38, v76, v94
	v_mfma_f32_32x32x16_bf16 v[18:33], v[34:37], v[46:49], v[18:33]
	v_max3_f32 v34, v39, v95, v79
	v_max3_f32 v35, v38, v78, v96
	v_max3_f32 v34, v34, v97, v81
	v_add_f32_e32 v36, v160, v161
	v_max3_f32 v34, v35, v80, v34
	v_add_f32_e32 v128, v128, v36
	v_cmp_lt_f32_e32 vcc, s33, v34
	s_waitcnt lgkmcnt(0)
	v_mfma_f32_32x32x16_bf16 v[2:17], v[134:137], v[46:49], v[2:17]
	s_cbranch_vccz .LBB0_401
	v_mov_b32_e32 v35, v34
	s_nop 1
	v_permlane32_swap_b32 v34, v35
	s_nop 1
	s_nop 0
	v_max3_f32 v36, v34, v35, 0
	v_exp_f32_e64 v38, -v36
	v_add_f32_e32 v127, v127, v36
	v_xor_b32_e32 v34, 0x80000000, v127
	v_pk_add_f32 v[82:83], v[82:83], v[36:37] op_sel_hi:[1,0] neg_lo:[0,1] neg_hi:[0,1]
	v_pk_add_f32 v[66:67], v[66:67], v[36:37] op_sel_hi:[1,0] neg_lo:[0,1] neg_hi:[0,1]
	v_pk_add_f32 v[84:85], v[84:85], v[36:37] op_sel_hi:[1,0] neg_lo:[0,1] neg_hi:[0,1]
	v_pk_add_f32 v[68:69], v[68:69], v[36:37] op_sel_hi:[1,0] neg_lo:[0,1] neg_hi:[0,1]
	v_pk_add_f32 v[86:87], v[86:87], v[36:37] op_sel_hi:[1,0] neg_lo:[0,1] neg_hi:[0,1]
	v_pk_add_f32 v[70:71], v[70:71], v[36:37] op_sel_hi:[1,0] neg_lo:[0,1] neg_hi:[0,1]
	v_pk_add_f32 v[88:89], v[88:89], v[36:37] op_sel_hi:[1,0] neg_lo:[0,1] neg_hi:[0,1]
	v_pk_add_f32 v[72:73], v[72:73], v[36:37] op_sel_hi:[1,0] neg_lo:[0,1] neg_hi:[0,1]
	v_pk_add_f32 v[90:91], v[90:91], v[36:37] op_sel_hi:[1,0] neg_lo:[0,1] neg_hi:[0,1]
	v_pk_add_f32 v[74:75], v[74:75], v[36:37] op_sel_hi:[1,0] neg_lo:[0,1] neg_hi:[0,1]
	v_pk_add_f32 v[92:93], v[92:93], v[36:37] op_sel_hi:[1,0] neg_lo:[0,1] neg_hi:[0,1]
	v_pk_add_f32 v[76:77], v[76:77], v[36:37] op_sel_hi:[1,0] neg_lo:[0,1] neg_hi:[0,1]
	v_pk_add_f32 v[94:95], v[94:95], v[36:37] op_sel_hi:[1,0] neg_lo:[0,1] neg_hi:[0,1]
	v_pk_add_f32 v[78:79], v[78:79], v[36:37] op_sel_hi:[1,0] neg_lo:[0,1] neg_hi:[0,1]
	v_pk_add_f32 v[96:97], v[96:97], v[36:37] op_sel_hi:[1,0] neg_lo:[0,1] neg_hi:[0,1]
	v_pk_add_f32 v[80:81], v[80:81], v[36:37] op_sel_hi:[1,0] neg_lo:[0,1] neg_hi:[0,1]
	v_pk_mul_f32 v[32:33], v[32:33], v[38:39] op_sel_hi:[1,0]
	v_pk_mul_f32 v[30:31], v[30:31], v[38:39] op_sel_hi:[1,0]
	v_pk_mul_f32 v[28:29], v[28:29], v[38:39] op_sel_hi:[1,0]
	v_pk_mul_f32 v[26:27], v[26:27], v[38:39] op_sel_hi:[1,0]
	v_pk_mul_f32 v[24:25], v[24:25], v[38:39] op_sel_hi:[1,0]
	v_pk_mul_f32 v[22:23], v[22:23], v[38:39] op_sel_hi:[1,0]
	v_pk_mul_f32 v[20:21], v[20:21], v[38:39] op_sel_hi:[1,0]
	v_pk_mul_f32 v[18:19], v[18:19], v[38:39] op_sel_hi:[1,0]
	v_pk_mul_f32 v[16:17], v[16:17], v[38:39] op_sel_hi:[1,0]
	v_pk_mul_f32 v[14:15], v[14:15], v[38:39] op_sel_hi:[1,0]
	v_pk_mul_f32 v[12:13], v[12:13], v[38:39] op_sel_hi:[1,0]
	v_pk_mul_f32 v[10:11], v[10:11], v[38:39] op_sel_hi:[1,0]
	v_pk_mul_f32 v[8:9], v[8:9], v[38:39] op_sel_hi:[1,0]
	v_pk_mul_f32 v[6:7], v[6:7], v[38:39] op_sel_hi:[1,0]
	v_pk_mul_f32 v[4:5], v[4:5], v[38:39] op_sel_hi:[1,0]
	v_pk_mul_f32 v[2:3], v[2:3], v[38:39] op_sel_hi:[1,0]
	v_mul_f32_e32 v128, v128, v38
	v_mov_b32_e32 v35, v34
	v_mov_b32_e32 v36, v34
	v_mov_b32_e32 v37, v34
	v_mov_b32_e32 v38, v34
	v_mov_b32_e32 v39, v34
	v_mov_b32_e32 v40, v34
	v_mov_b32_e32 v41, v34
	v_mov_b32_e32 v42, v34
	v_mov_b32_e32 v43, v34
	v_mov_b32_e32 v44, v34
	v_mov_b32_e32 v45, v34
	v_mov_b32_e32 v46, v34
	v_mov_b32_e32 v47, v34
	v_mov_b32_e32 v48, v34
	v_mov_b32_e32 v49, v34
	v_mov_b32_e32 v50, v34
	v_mov_b32_e32 v51, v34
	v_mov_b32_e32 v52, v34
	v_mov_b32_e32 v53, v34
	v_mov_b32_e32 v54, v34
	v_mov_b32_e32 v55, v34
	v_mov_b32_e32 v56, v34
	v_mov_b32_e32 v57, v34
	v_mov_b32_e32 v58, v34
	v_mov_b32_e32 v59, v34
	v_mov_b32_e32 v60, v34
	v_mov_b32_e32 v61, v34
	v_mov_b32_e32 v62, v34
	v_mov_b32_e32 v63, v34
	v_mov_b32_e32 v64, v34
	v_mov_b32_e32 v65, v34
	s_branch .LBB0_402

.LBB0_402:
	v_exp_f32_e32 v129, v82
	s_setprio 0
	v_exp_f32_e32 v146, v83
	v_exp_f32_e32 v147, v84
	v_exp_f32_e32 v148, v85
	v_exp_f32_e32 v149, v86
	v_exp_f32_e32 v150, v87
	v_exp_f32_e32 v151, v88
	v_exp_f32_e32 v152, v89
	v_exp_f32_e32 v153, v90
	v_exp_f32_e32 v154, v91
	v_exp_f32_e32 v155, v92
	v_exp_f32_e32 v156, v93
	v_exp_f32_e32 v157, v94
	v_exp_f32_e32 v158, v95
	v_exp_f32_e32 v159, v96
	v_exp_f32_e32 v160, v97
	s_add_i32 s58, s55, 4
	s_and_b32 s59, s56, 0xf00000
	s_and_b32 s58, s58, 3
	s_lshl_b32 s78, s59, 1
	v_lshl_add_u64 v[82:83], v[116:117], 0, s[78:79]
	s_mul_i32 s58, s58, 0x38000
	s_mov_b32 s59, s79
	s_add_i32 s60, s57, s5
	v_lshl_add_u64 v[82:83], v[82:83], 0, s[58:59]
	s_mov_b32 m0, s60
	s_waitcnt vmcnt(0)
	s_barrier
	s_setprio 3
	global_load_lds_dwordx4 v[82:83], off
	v_lshl_add_u64 v[82:83], v[118:119], 0, s[78:79]
	v_lshl_add_u64 v[82:83], v[82:83], 0, s[58:59]
	s_add_i32 m0, s60, 0x2000
	s_nop 0
	global_load_lds_dwordx4 v[82:83], off
	v_add_u32_e32 v142, s54, v126
	ds_read_b128 v[130:133], v142
	ds_read_b128 v[134:137], v142 offset:2048
	v_exp_f32_e32 v161, v66
	v_exp_f32_e32 v162, v67
	v_exp_f32_e32 v163, v68
	v_exp_f32_e32 v164, v69
	ds_read_b128 v[66:69], v142 offset:4096
	v_exp_f32_e32 v165, v70
	v_exp_f32_e32 v166, v71
	s_waitcnt lgkmcnt(0)
	v_mfma_f32_32x32x16_bf16 v[82:97], v[130:133], v[110:113], v[34:49]
	v_exp_f32_e32 v167, v72
	v_exp_f32_e32 v168, v73
	ds_read_b128 v[70:73], v142 offset:6144
	v_exp_f32_e32 v169, v74
	v_exp_f32_e32 v170, v75
	v_exp_f32_e32 v171, v76
	v_exp_f32_e32 v172, v77
	v_mfma_f32_32x32x16_bf16 v[82:97], v[134:137], v[106:109], v[82:97]
	ds_read_b128 v[130:133], v142 offset:512
	ds_read_b128 v[134:137], v142 offset:2560
	ds_read_b128 v[138:141], v142 offset:4608
	ds_read_b128 v[142:145], v142 offset:6656
	v_exp_f32_e32 v173, v78
	v_exp_f32_e32 v174, v79
	v_exp_f32_e32 v175, v80
	v_exp_f32_e32 v176, v81
	v_mfma_f32_32x32x16_bf16 v[82:97], v[66:69], v[102:105], v[82:97]
	v_add_f32_e32 v66, v129, v146
	v_add_f32_e32 v66, v147, v66
	v_add_f32_e32 v66, v148, v66
	v_add_f32_e32 v66, v149, v66
	v_add_f32_e32 v66, v150, v66
	v_add_f32_e32 v66, v151, v66
	v_add_f32_e32 v66, v152, v66
	v_add_f32_e32 v66, v153, v66
	s_waitcnt lgkmcnt(0)
	v_mfma_f32_32x32x16_bf16 v[82:97], v[70:73], v[98:101], v[82:97]
	v_add_f32_e32 v177, v154, v66
	v_mfma_f32_32x32x16_bf16 v[66:81], v[130:133], v[110:113], v[34:49]
	v_add_f32_e32 v130, v155, v177
	v_add_f32_e32 v130, v156, v130
	v_add_f32_e32 v130, v157, v130
	v_add_f32_e32 v130, v158, v130
	v_add_f32_e32 v130, v159, v130
	v_add_f32_e32 v130, v160, v130
	v_add_f32_e32 v130, v161, v130
	v_mfma_f32_32x32x16_bf16 v[66:81], v[134:137], v[106:109], v[66:81]
	v_add_f32_e32 v130, v162, v130
	v_add_f32_e32 v130, v163, v130
	v_add_f32_e32 v130, v164, v130
	v_add_f32_e32 v130, v165, v130
	v_add_f32_e32 v130, v166, v130
	v_add_f32_e32 v130, v167, v130
	s_setprio 2
	v_add_f32_e32 v130, v168, v130
	v_mfma_f32_32x32x16_bf16 v[66:81], v[138:141], v[102:105], v[66:81]
	v_add_f32_e32 v130, v169, v130
	v_add_f32_e32 v130, v170, v130
	v_add_f32_e32 v130, v171, v130
	v_add_f32_e32 v130, v172, v130
	v_add_f32_e32 v130, v173, v130
	v_add_f32_e32 v130, v174, v130
	v_add_f32_e32 v177, v175, v130
	v_mfma_f32_32x32x16_bf16 v[66:81], v[142:145], v[98:101], v[66:81]
	v_cvt_pk_bf16_f32 v130, v129, v146
	v_cvt_pk_bf16_f32 v131, v147, v148
	v_cvt_pk_bf16_f32 v132, v149, v150
	v_cvt_pk_bf16_f32 v133, v151, v152
	v_cvt_pk_bf16_f32 v134, v153, v154
	v_cvt_pk_bf16_f32 v135, v155, v156
	v_cvt_pk_bf16_f32 v136, v157, v158
	v_cvt_pk_bf16_f32 v137, v159, v160
	v_cvt_pk_bf16_f32 v138, v161, v162
	v_cvt_pk_bf16_f32 v139, v163, v164
	v_cvt_pk_bf16_f32 v140, v165, v166
	v_cvt_pk_bf16_f32 v141, v167, v168
	v_cvt_pk_bf16_f32 v142, v169, v170
	v_cvt_pk_bf16_f32 v143, v171, v172
	v_cvt_pk_bf16_f32 v144, v173, v174
	v_cvt_pk_bf16_f32 v145, v175, v176
	v_add_u32_e32 v129, s53, v125
	ds_read_b64_tr_b16 v[146:147], v129 offset:8192
	ds_read_b64_tr_b16 v[148:149], v129 offset:8704
	ds_read_b64_tr_b16 v[150:151], v129 offset:12288
	s_waitcnt lgkmcnt(1)
	v_mfma_f32_32x32x16_bf16 v[18:33], v[146:149], v[130:133], v[18:33]
	ds_read_b64_tr_b16 v[152:153], v129 offset:12800
	ds_read_b64_tr_b16 v[146:147], v129 offset:9216
	s_waitcnt lgkmcnt(1)
	v_mfma_f32_32x32x16_bf16 v[2:17], v[150:153], v[130:133], v[2:17]
	ds_read_b64_tr_b16 v[148:149], v129 offset:9728
	ds_read_b64_tr_b16 v[130:131], v129 offset:13312
	s_waitcnt lgkmcnt(1)
	v_mfma_f32_32x32x16_bf16 v[18:33], v[146:149], v[134:137], v[18:33]
	ds_read_b64_tr_b16 v[132:133], v129 offset:13824
	ds_read_b64_tr_b16 v[146:147], v129 offset:10240
	s_waitcnt lgkmcnt(1)
	v_mfma_f32_32x32x16_bf16 v[2:17], v[130:133], v[134:137], v[2:17]
	ds_read_b64_tr_b16 v[148:149], v129 offset:10752
	ds_read_b64_tr_b16 v[130:131], v129 offset:11264
	ds_read_b64_tr_b16 v[132:133], v129 offset:11776
	ds_read_b64_tr_b16 v[134:135], v129 offset:14336
	ds_read_b64_tr_b16 v[136:137], v129 offset:14848
	ds_read_b64_tr_b16 v[150:151], v129 offset:15360
	ds_read_b64_tr_b16 v[152:153], v129 offset:15872
	v_max_f32_e32 v129, v67, v67
	s_waitcnt lgkmcnt(6)
	v_mfma_f32_32x32x16_bf16 v[18:33], v[146:149], v[138:141], v[18:33]
	v_max_f32_e32 v146, v83, v83
	v_max_f32_e32 v129, v146, v129
	v_max3_f32 v146, v82, v66, v84
	v_max3_f32 v129, v129, v85, v69
	v_max3_f32 v146, v146, v68, v86
	v_max3_f32 v129, v129, v87, v71
	v_max3_f32 v129, v129, v89, v73
	s_waitcnt lgkmcnt(2)
	s_setprio 1
	v_mfma_f32_32x32x16_bf16 v[2:17], v[134:137], v[138:141], v[2:17]
	v_max3_f32 v134, v146, v70, v88
	v_max3_f32 v134, v134, v72, v90
	v_max3_f32 v129, v129, v91, v75
	v_max3_f32 v134, v134, v74, v92
	v_max3_f32 v129, v129, v93, v77
	v_max3_f32 v134, v134, v76, v94
	v_max3_f32 v129, v129, v95, v79
	v_mfma_f32_32x32x16_bf16 v[18:33], v[130:133], v[142:145], v[18:33]
	v_max3_f32 v130, v134, v78, v96
	v_max3_f32 v129, v129, v97, v81
	v_add_f32_e32 v131, v176, v177
	v_max3_f32 v129, v130, v80, v129
	v_add_f32_e32 v128, v128, v131
	v_cmp_lt_f32_e32 vcc, s33, v129
	s_waitcnt lgkmcnt(0)
	v_mfma_f32_32x32x16_bf16 v[2:17], v[150:153], v[142:145], v[2:17]
	s_cbranch_vccz .LBB0_404
	v_mov_b32_e32 v34, v129
	s_nop 1
	v_permlane32_swap_b32 v129, v34
	s_nop 1
	s_nop 0
	v_max3_f32 v36, v129, v34, 0
	v_exp_f32_e64 v38, -v36
	v_add_f32_e32 v127, v127, v36
	v_xor_b32_e32 v34, 0x80000000, v127
	v_pk_add_f32 v[82:83], v[82:83], v[36:37] op_sel_hi:[1,0] neg_lo:[0,1] neg_hi:[0,1]
	v_pk_add_f32 v[84:85], v[84:85], v[36:37] op_sel_hi:[1,0] neg_lo:[0,1] neg_hi:[0,1]
	v_pk_add_f32 v[86:87], v[86:87], v[36:37] op_sel_hi:[1,0] neg_lo:[0,1] neg_hi:[0,1]
	v_pk_add_f32 v[88:89], v[88:89], v[36:37] op_sel_hi:[1,0] neg_lo:[0,1] neg_hi:[0,1]
	v_pk_add_f32 v[90:91], v[90:91], v[36:37] op_sel_hi:[1,0] neg_lo:[0,1] neg_hi:[0,1]
	v_pk_add_f32 v[92:93], v[92:93], v[36:37] op_sel_hi:[1,0] neg_lo:[0,1] neg_hi:[0,1]
	v_pk_add_f32 v[94:95], v[94:95], v[36:37] op_sel_hi:[1,0] neg_lo:[0,1] neg_hi:[0,1]
	v_pk_add_f32 v[96:97], v[96:97], v[36:37] op_sel_hi:[1,0] neg_lo:[0,1] neg_hi:[0,1]
	v_sub_f32_e32 v81, v81, v36
	v_sub_f32_e32 v80, v80, v36
	v_sub_f32_e32 v79, v79, v36
	v_sub_f32_e32 v78, v78, v36
	v_sub_f32_e32 v77, v77, v36
	v_sub_f32_e32 v76, v76, v36
	v_sub_f32_e32 v75, v75, v36
	v_sub_f32_e32 v74, v74, v36
	v_sub_f32_e32 v73, v73, v36
	v_sub_f32_e32 v72, v72, v36
	v_sub_f32_e32 v71, v71, v36
	v_sub_f32_e32 v70, v70, v36
	v_sub_f32_e32 v69, v69, v36
	v_sub_f32_e32 v68, v68, v36
	v_sub_f32_e32 v67, v67, v36
	v_sub_f32_e32 v66, v66, v36
	v_pk_mul_f32 v[32:33], v[32:33], v[38:39] op_sel_hi:[1,0]
	v_pk_mul_f32 v[30:31], v[30:31], v[38:39] op_sel_hi:[1,0]
	v_pk_mul_f32 v[28:29], v[28:29], v[38:39] op_sel_hi:[1,0]
	v_pk_mul_f32 v[26:27], v[26:27], v[38:39] op_sel_hi:[1,0]
	v_pk_mul_f32 v[24:25], v[24:25], v[38:39] op_sel_hi:[1,0]
	v_pk_mul_f32 v[22:23], v[22:23], v[38:39] op_sel_hi:[1,0]
	v_pk_mul_f32 v[20:21], v[20:21], v[38:39] op_sel_hi:[1,0]
	v_pk_mul_f32 v[18:19], v[18:19], v[38:39] op_sel_hi:[1,0]
	v_pk_mul_f32 v[16:17], v[16:17], v[38:39] op_sel_hi:[1,0]
	v_pk_mul_f32 v[14:15], v[14:15], v[38:39] op_sel_hi:[1,0]
	v_pk_mul_f32 v[12:13], v[12:13], v[38:39] op_sel_hi:[1,0]
	v_pk_mul_f32 v[10:11], v[10:11], v[38:39] op_sel_hi:[1,0]
	v_pk_mul_f32 v[8:9], v[8:9], v[38:39] op_sel_hi:[1,0]
	v_pk_mul_f32 v[6:7], v[6:7], v[38:39] op_sel_hi:[1,0]
	v_pk_mul_f32 v[4:5], v[4:5], v[38:39] op_sel_hi:[1,0]
	v_pk_mul_f32 v[2:3], v[2:3], v[38:39] op_sel_hi:[1,0]
	v_mul_f32_e32 v128, v128, v38
	v_mov_b32_e32 v35, v34
	v_mov_b32_e32 v36, v34
	v_mov_b32_e32 v37, v34
	v_mov_b32_e32 v38, v34
	v_mov_b32_e32 v39, v34
	v_mov_b32_e32 v40, v34
	v_mov_b32_e32 v41, v34
	v_mov_b32_e32 v42, v34
	v_mov_b32_e32 v43, v34
	v_mov_b32_e32 v44, v34
	v_mov_b32_e32 v45, v34
	v_mov_b32_e32 v46, v34
	v_mov_b32_e32 v47, v34
	v_mov_b32_e32 v48, v34
	v_mov_b32_e32 v49, v34
	v_mov_b32_e32 v50, v34
	v_mov_b32_e32 v51, v34
	v_mov_b32_e32 v52, v34
	v_mov_b32_e32 v53, v34
	v_mov_b32_e32 v54, v34
	v_mov_b32_e32 v55, v34
	v_mov_b32_e32 v56, v34
	v_mov_b32_e32 v57, v34
	v_mov_b32_e32 v58, v34
	v_mov_b32_e32 v59, v34
	v_mov_b32_e32 v60, v34
	v_mov_b32_e32 v61, v34
	v_mov_b32_e32 v62, v34
	v_mov_b32_e32 v63, v34
	v_mov_b32_e32 v64, v34
	v_mov_b32_e32 v65, v34
.LBB0_404:
	v_exp_f32_e32 v129, v82
	s_setprio 0
	v_exp_f32_e32 v131, v83
	v_exp_f32_e32 v132, v84
	v_exp_f32_e32 v135, v85
	v_exp_f32_e32 v136, v86
	v_exp_f32_e32 v139, v87
	v_exp_f32_e32 v140, v88
	v_exp_f32_e32 v143, v89
	v_exp_f32_e32 v130, v90
	v_exp_f32_e32 v133, v91
	v_exp_f32_e32 v134, v92
	v_exp_f32_e32 v137, v93
	v_exp_f32_e32 v138, v94
	v_exp_f32_e32 v141, v95
	v_exp_f32_e32 v142, v96
	v_exp_f32_e32 v144, v97
	s_waitcnt vmcnt(0)
	s_add_i32 s55, s55, 2
	s_add_i32 s56, s56, 0x80000
	s_cmp_lt_u32 s55, 29
	s_barrier
	s_cbranch_scc0 .LBB0_407
	s_mov_b32 s72, s29
	s_mov_b32 s29, s30
	s_branch .LBB0_399

.LBB0_422:
	s_setprio 3
	s_add_i32 s41, s58, 0xfffc0000
	s_mov_b32 s30, s28
	s_mov_b32 s28, s40
	s_add_i32 s40, s57, -1
	s_and_b32 s41, s41, 0xf00000
	s_and_b32 s55, s40, 3
	s_lshl_b32 s78, s41, 1
	s_add_i32 s53, s29, 0
	v_lshl_add_u64 v[34:35], v[128:129], 0, s[78:79]
	s_lshl_b32 s40, s55, 16
	s_mov_b32 s41, s79
	s_add_i32 s54, s53, s27
	v_lshl_add_u64 v[34:35], v[34:35], 0, s[40:41]
	s_mov_b32 m0, s54
	v_cndmask_b32_e64 v0, 0, 1, s[38:39]
	global_load_lds_dwordx4 v[34:35], off
	v_cmp_ne_u32_e64 s[40:41], 1, v0
	s_andn2_b64 vcc, exec, s[38:39]
	s_cbranch_vccnz .LBB0_424
	v_lshl_add_u64 v[34:35], v[124:125], 0, s[78:79]
	s_mul_i32 s60, s55, 0x38000
	s_mov_b32 s61, s79
	s_add_i32 s56, s53, s5
	v_lshl_add_u64 v[34:35], v[34:35], 0, s[60:61]
	s_add_i32 m0, s56, 0x2000
	s_nop 0
	global_load_lds_dwordx4 v[34:35], off
.LBB0_424:
	s_lshl_b32 s55, s55, 15
	v_lshl_add_u64 v[34:35], v[130:131], 0, s[78:79]
	s_lshl_b32 s78, s55, 1
	v_lshl_add_u64 v[34:35], v[34:35], 0, s[78:79]
	s_add_i32 s55, s54, 0x3000
	v_lshl_add_u64 v[34:35], v[34:35], 0, s[24:25]
	s_mov_b32 m0, s55
	s_nop 0
	global_load_lds_dwordx4 v[34:35], off
	s_add_i32 s56, s30, 0
	v_add_u32_e32 v0, s56, v134
	ds_read_b128 v[34:37], v0
	v_exp_f32_e32 v153, v66
	v_exp_f32_e32 v166, v67
	v_exp_f32_e32 v167, v68
	v_exp_f32_e32 v168, v69
	v_exp_f32_e32 v169, v70
	v_exp_f32_e32 v170, v71
	v_exp_f32_e32 v171, v72
	v_exp_f32_e32 v172, v73
	s_waitcnt lgkmcnt(0)
	v_mfma_f32_32x32x16_bf16 v[82:97], v[34:37], v[118:121], v[50:65]
	ds_read_b128 v[34:37], v0 offset:2048
	ds_read_b128 v[38:41], v0 offset:4096
	v_exp_f32_e32 v173, v74
	v_exp_f32_e32 v174, v75
	v_exp_f32_e32 v175, v76
	v_exp_f32_e32 v176, v77
	v_exp_f32_e32 v177, v78
	v_exp_f32_e32 v178, v79
	s_waitcnt lgkmcnt(0)
	v_mfma_f32_32x32x16_bf16 v[82:97], v[34:37], v[114:117], v[82:97]
	ds_read_b128 v[34:37], v0 offset:6144
	v_exp_f32_e32 v179, v80
	v_exp_f32_e32 v180, v81
	v_mfma_f32_32x32x16_bf16 v[82:97], v[38:41], v[110:113], v[82:97]
	ds_read_b128 v[38:41], v0 offset:8192
	s_waitcnt lgkmcnt(0)
	v_mfma_f32_32x32x16_bf16 v[82:97], v[34:37], v[106:109], v[82:97]
	v_add_f32_e32 v34, v141, v146
	v_add_f32_e32 v66, v138, v34
	ds_read_b128 v[34:37], v0 offset:10240
	s_setprio 2
	v_mfma_f32_32x32x16_bf16 v[82:97], v[38:41], v[102:105], v[82:97]
	ds_read_b128 v[38:41], v0 offset:512
	ds_read_b128 v[42:45], v0 offset:2560
	ds_read_b128 v[46:49], v0 offset:4608
	ds_read_b128 v[154:157], v0 offset:6656
	ds_read_b128 v[158:161], v0 offset:8704
	ds_read_b128 v[162:165], v0 offset:10752
	v_add_f32_e32 v0, v142, v66
	v_add_f32_e32 v0, v143, v0
	v_add_f32_e32 v0, v147, v0
	v_add_f32_e32 v0, v148, v0
	v_add_f32_e32 v0, v151, v0
	v_add_f32_e32 v0, v137, v0
	s_waitcnt lgkmcnt(0)
	v_mfma_f32_32x32x16_bf16 v[66:81], v[38:41], v[118:121], v[50:65]
	v_add_f32_e32 v0, v139, v0
	v_add_f32_e32 v0, v140, v0
	v_add_f32_e32 v0, v144, v0
	v_add_f32_e32 v0, v145, v0
	v_add_f32_e32 v0, v149, v0
	v_add_f32_e32 v0, v150, v0
	v_add_f32_e32 v0, v152, v0
	v_mfma_f32_32x32x16_bf16 v[66:81], v[42:45], v[114:117], v[66:81]
	v_add_f32_e32 v0, v153, v0
	v_add_f32_e32 v0, v166, v0
	v_add_f32_e32 v0, v167, v0
	v_add_f32_e32 v0, v168, v0
	v_add_f32_e32 v0, v169, v0
	v_add_f32_e32 v0, v170, v0
	v_add_f32_e32 v0, v171, v0
	v_mfma_f32_32x32x16_bf16 v[66:81], v[46:49], v[110:113], v[66:81]
	v_add_f32_e32 v0, v172, v0
	v_add_f32_e32 v0, v173, v0
	v_add_f32_e32 v0, v174, v0
	v_add_f32_e32 v0, v175, v0
	v_add_f32_e32 v0, v176, v0
	v_add_f32_e32 v0, v177, v0
	v_add_f32_e32 v0, v178, v0
	v_mfma_f32_32x32x16_bf16 v[66:81], v[154:157], v[106:109], v[66:81]
	v_add_f32_e32 v181, v179, v0
	v_cvt_pk_bf16_f32 v38, v137, v139
	v_cvt_pk_bf16_f32 v39, v140, v144
	v_cvt_pk_bf16_f32 v40, v145, v149
	v_cvt_pk_bf16_f32 v41, v150, v152
	v_cvt_pk_bf16_f32 v42, v153, v166
	v_cvt_pk_bf16_f32 v43, v167, v168
	v_mfma_f32_32x32x16_bf16 v[66:81], v[158:161], v[102:105], v[66:81]
	v_cvt_pk_bf16_f32 v44, v169, v170
	v_cvt_pk_bf16_f32 v45, v171, v172
	v_cvt_pk_bf16_f32 v46, v173, v174
	v_cvt_pk_bf16_f32 v47, v175, v176
	v_cvt_pk_bf16_f32 v48, v177, v178
	v_cvt_pk_bf16_f32 v49, v179, v180
	v_mfma_f32_32x32x16_bf16 v[82:97], v[34:37], v[98:101], v[82:97]
	v_cvt_pk_bf16_f32 v34, v141, v146
	v_cvt_pk_bf16_f32 v35, v138, v142
	v_cvt_pk_bf16_f32 v36, v143, v147
	v_cvt_pk_bf16_f32 v37, v148, v151
	v_mfma_f32_32x32x16_bf16 v[66:81], v[162:165], v[98:101], v[66:81]
	s_add_i32 s59, s28, 0
	v_add_u32_e32 v0, s59, v133
	ds_read_b64_tr_b16 v[138:139], v0 offset:12288
	ds_read_b64_tr_b16 v[140:141], v0 offset:12800
	ds_read_b64_tr_b16 v[142:143], v0 offset:16384
	s_nop 5
	v_max_f32_e32 v137, v67, v67
	s_waitcnt lgkmcnt(1)
	v_mfma_f32_32x32x16_bf16 v[18:33], v[138:141], v[34:37], v[18:33]
	ds_read_b64_tr_b16 v[144:145], v0 offset:16896
	ds_read_b64_tr_b16 v[138:139], v0 offset:13312
	s_waitcnt lgkmcnt(1)
	v_mfma_f32_32x32x16_bf16 v[2:17], v[142:145], v[34:37], v[2:17]
	ds_read_b64_tr_b16 v[140:141], v0 offset:13824
	ds_read_b64_tr_b16 v[34:35], v0 offset:17408
	s_setprio 1
	s_waitcnt lgkmcnt(1)
	v_mfma_f32_32x32x16_bf16 v[18:33], v[138:141], v[38:41], v[18:33]
	ds_read_b64_tr_b16 v[36:37], v0 offset:17920
	ds_read_b64_tr_b16 v[138:139], v0 offset:14336
	s_waitcnt lgkmcnt(1)
	v_mfma_f32_32x32x16_bf16 v[2:17], v[34:37], v[38:41], v[2:17]
	ds_read_b64_tr_b16 v[140:141], v0 offset:14848
	ds_read_b64_tr_b16 v[34:35], v0 offset:15360
	ds_read_b64_tr_b16 v[36:37], v0 offset:15872
	ds_read_b64_tr_b16 v[38:39], v0 offset:18432
	ds_read_b64_tr_b16 v[40:41], v0 offset:18944
	ds_read_b64_tr_b16 v[142:143], v0 offset:19456
	ds_read_b64_tr_b16 v[144:145], v0 offset:19968
	s_waitcnt lgkmcnt(6)
	v_mfma_f32_32x32x16_bf16 v[18:33], v[138:141], v[42:45], v[18:33]
	v_max_f32_e32 v138, v83, v83
	v_max_f32_e32 v137, v138, v137
	v_max3_f32 v138, v82, v66, v84
	v_max3_f32 v137, v137, v85, v69
	v_max3_f32 v138, v138, v68, v86
	v_max3_f32 v137, v137, v87, v71
	s_waitcnt lgkmcnt(2)
	v_mfma_f32_32x32x16_bf16 v[2:17], v[38:41], v[42:45], v[2:17]
	v_max3_f32 v38, v138, v70, v88
	v_max3_f32 v39, v137, v89, v73
	v_max3_f32 v38, v38, v72, v90
	v_max3_f32 v39, v39, v91, v75
	v_max3_f32 v38, v38, v74, v92
	v_max3_f32 v39, v39, v93, v77
	v_max3_f32 v38, v38, v76, v94
	v_mfma_f32_32x32x16_bf16 v[18:33], v[34:37], v[46:49], v[18:33]
	v_max3_f32 v34, v39, v95, v79
	v_max3_f32 v35, v38, v78, v96
	v_max3_f32 v34, v34, v97, v81
	v_add_f32_e32 v36, v180, v181
	v_max3_f32 v34, v35, v80, v34
	v_add_f32_e32 v136, v136, v36
	v_cmp_lt_f32_e32 vcc, s33, v34
	s_waitcnt lgkmcnt(0)
	v_mfma_f32_32x32x16_bf16 v[2:17], v[142:145], v[46:49], v[2:17]
	s_cbranch_vccz .LBB0_426
	v_mov_b32_e32 v35, v34
	s_nop 1
	v_permlane32_swap_b32 v34, v35
	s_nop 1
	s_nop 0
	v_max3_f32 v36, v34, v35, 0
	v_exp_f32_e64 v38, -v36
	v_add_f32_e32 v135, v135, v36
	v_xor_b32_e32 v34, 0x80000000, v135
	v_pk_add_f32 v[82:83], v[82:83], v[36:37] op_sel_hi:[1,0] neg_lo:[0,1] neg_hi:[0,1]
	v_pk_add_f32 v[84:85], v[84:85], v[36:37] op_sel_hi:[1,0] neg_lo:[0,1] neg_hi:[0,1]
	v_pk_add_f32 v[86:87], v[86:87], v[36:37] op_sel_hi:[1,0] neg_lo:[0,1] neg_hi:[0,1]
	v_pk_add_f32 v[88:89], v[88:89], v[36:37] op_sel_hi:[1,0] neg_lo:[0,1] neg_hi:[0,1]
	v_pk_add_f32 v[90:91], v[90:91], v[36:37] op_sel_hi:[1,0] neg_lo:[0,1] neg_hi:[0,1]
	v_pk_add_f32 v[92:93], v[92:93], v[36:37] op_sel_hi:[1,0] neg_lo:[0,1] neg_hi:[0,1]
	v_pk_add_f32 v[94:95], v[94:95], v[36:37] op_sel_hi:[1,0] neg_lo:[0,1] neg_hi:[0,1]
	v_pk_add_f32 v[96:97], v[96:97], v[36:37] op_sel_hi:[1,0] neg_lo:[0,1] neg_hi:[0,1]
	v_sub_f32_e32 v81, v81, v36
	v_sub_f32_e32 v80, v80, v36
	v_sub_f32_e32 v79, v79, v36
	v_sub_f32_e32 v78, v78, v36
	v_sub_f32_e32 v77, v77, v36
	v_sub_f32_e32 v76, v76, v36
	v_sub_f32_e32 v75, v75, v36
	v_sub_f32_e32 v74, v74, v36
	v_sub_f32_e32 v73, v73, v36
	v_sub_f32_e32 v72, v72, v36
	v_sub_f32_e32 v71, v71, v36
	v_sub_f32_e32 v70, v70, v36
	v_sub_f32_e32 v69, v69, v36
	v_sub_f32_e32 v68, v68, v36
	v_sub_f32_e32 v67, v67, v36
	v_sub_f32_e32 v66, v66, v36
	v_pk_mul_f32 v[32:33], v[32:33], v[38:39] op_sel_hi:[1,0]
	v_pk_mul_f32 v[30:31], v[30:31], v[38:39] op_sel_hi:[1,0]
	v_pk_mul_f32 v[28:29], v[28:29], v[38:39] op_sel_hi:[1,0]
	v_pk_mul_f32 v[26:27], v[26:27], v[38:39] op_sel_hi:[1,0]
	v_pk_mul_f32 v[24:25], v[24:25], v[38:39] op_sel_hi:[1,0]
	v_pk_mul_f32 v[22:23], v[22:23], v[38:39] op_sel_hi:[1,0]
	v_pk_mul_f32 v[20:21], v[20:21], v[38:39] op_sel_hi:[1,0]
	v_pk_mul_f32 v[18:19], v[18:19], v[38:39] op_sel_hi:[1,0]
	v_pk_mul_f32 v[16:17], v[16:17], v[38:39] op_sel_hi:[1,0]
	v_pk_mul_f32 v[14:15], v[14:15], v[38:39] op_sel_hi:[1,0]
	v_pk_mul_f32 v[12:13], v[12:13], v[38:39] op_sel_hi:[1,0]
	v_pk_mul_f32 v[10:11], v[10:11], v[38:39] op_sel_hi:[1,0]
	v_pk_mul_f32 v[8:9], v[8:9], v[38:39] op_sel_hi:[1,0]
	v_pk_mul_f32 v[6:7], v[6:7], v[38:39] op_sel_hi:[1,0]
	v_pk_mul_f32 v[4:5], v[4:5], v[38:39] op_sel_hi:[1,0]
	v_pk_mul_f32 v[2:3], v[2:3], v[38:39] op_sel_hi:[1,0]
	v_mul_f32_e32 v136, v136, v38
	v_mov_b32_e32 v35, v34
	v_mov_b32_e32 v36, v34
	v_mov_b32_e32 v37, v34
	v_mov_b32_e32 v38, v34
	v_mov_b32_e32 v39, v34
	v_mov_b32_e32 v40, v34
	v_mov_b32_e32 v41, v34
	v_mov_b32_e32 v42, v34
	v_mov_b32_e32 v43, v34
	v_mov_b32_e32 v44, v34
	v_mov_b32_e32 v45, v34
	v_mov_b32_e32 v46, v34
	v_mov_b32_e32 v47, v34
	v_mov_b32_e32 v48, v34
	v_mov_b32_e32 v49, v34
	v_mov_b32_e32 v50, v34
	v_mov_b32_e32 v51, v34
	v_mov_b32_e32 v52, v34
	v_mov_b32_e32 v53, v34
	v_mov_b32_e32 v54, v34
	v_mov_b32_e32 v55, v34
	v_mov_b32_e32 v56, v34
	v_mov_b32_e32 v57, v34
	v_mov_b32_e32 v58, v34
	v_mov_b32_e32 v59, v34
	v_mov_b32_e32 v60, v34
	v_mov_b32_e32 v61, v34
	v_mov_b32_e32 v62, v34
	v_mov_b32_e32 v63, v34
	v_mov_b32_e32 v64, v34
	v_mov_b32_e32 v65, v34
	s_branch .LBB0_427

.LBB0_427:
	s_setprio 0
	s_add_i32 s60, s57, 4
	s_and_b32 s61, s58, 0xf00000
	s_and_b32 s60, s60, 3
	s_lshl_b32 s78, s61, 1
	v_lshl_add_u64 v[138:139], v[128:129], 0, s[78:79]
	s_lshl_b32 s62, s60, 16
	s_mov_b32 s63, s79
	s_add_i32 s61, s59, s27
	v_lshl_add_u64 v[138:139], v[138:139], 0, s[62:63]
	s_mov_b32 m0, s61
	s_waitcnt vmcnt(0)
	s_barrier
	s_setprio 3
	global_load_lds_dwordx4 v[138:139], off
	s_and_b64 vcc, exec, s[40:41]
	s_cbranch_vccnz .LBB0_429
	v_lshl_add_u64 v[138:139], v[124:125], 0, s[78:79]
	s_mul_i32 s40, s60, 0x38000
	s_mov_b32 s41, s79
	v_lshl_add_u64 v[138:139], v[138:139], 0, s[40:41]
	s_add_i32 s40, s59, s5
	s_add_i32 m0, s40, 0x2000
	s_nop 0
	global_load_lds_dwordx4 v[138:139], off
.LBB0_429:
	s_lshl_b32 s40, s60, 15
	v_exp_f32_e32 v137, v82
	v_exp_f32_e32 v162, v83
	v_lshl_add_u64 v[82:83], v[130:131], 0, s[78:79]
	s_lshl_b32 s78, s40, 1
	v_lshl_add_u64 v[82:83], v[82:83], 0, s[78:79]
	v_lshl_add_u64 v[82:83], v[82:83], 0, s[24:25]
	s_add_i32 m0, s61, 0x3000
	v_exp_f32_e32 v163, v84
	global_load_lds_dwordx4 v[82:83], off
	v_exp_f32_e32 v164, v85
	v_exp_f32_e32 v165, v86
	v_exp_f32_e32 v166, v87
	v_exp_f32_e32 v167, v88
	v_exp_f32_e32 v168, v89
	v_exp_f32_e32 v169, v90
	v_exp_f32_e32 v170, v91
	v_exp_f32_e32 v171, v92
	v_exp_f32_e32 v172, v93
	v_exp_f32_e32 v173, v94
	v_exp_f32_e32 v174, v95
	v_exp_f32_e32 v175, v96
	v_exp_f32_e32 v176, v97
	v_add_u32_e32 v158, s53, v134
	ds_read_b128 v[138:141], v158
	v_exp_f32_e32 v177, v66
	v_exp_f32_e32 v178, v67
	v_exp_f32_e32 v179, v68
	v_exp_f32_e32 v180, v69
	v_exp_f32_e32 v181, v70
	v_exp_f32_e32 v182, v71
	v_exp_f32_e32 v183, v72
	v_exp_f32_e32 v184, v73
	s_waitcnt lgkmcnt(0)
	v_mfma_f32_32x32x16_bf16 v[82:97], v[138:141], v[118:121], v[34:49]
	ds_read_b128 v[138:141], v158 offset:2048
	ds_read_b128 v[142:145], v158 offset:4096
	ds_read_b128 v[66:69], v158 offset:6144
	ds_read_b128 v[70:73], v158 offset:8192
	v_exp_f32_e32 v185, v74
	v_add_f32_e32 v74, v137, v162
	v_exp_f32_e32 v186, v75
	v_exp_f32_e32 v187, v76
	s_waitcnt lgkmcnt(0)
	v_mfma_f32_32x32x16_bf16 v[82:97], v[138:141], v[114:117], v[82:97]
	v_exp_f32_e32 v188, v77
	v_exp_f32_e32 v189, v78
	v_exp_f32_e32 v199, v79
	v_exp_f32_e32 v200, v80
	v_exp_f32_e32 v201, v81
	v_mfma_f32_32x32x16_bf16 v[82:97], v[142:145], v[110:113], v[82:97]
	v_mfma_f32_32x32x16_bf16 v[82:97], v[66:69], v[106:109], v[82:97]
	ds_read_b128 v[138:141], v158 offset:512
	ds_read_b128 v[66:69], v158 offset:10240
	ds_read_b128 v[142:145], v158 offset:2560
	ds_read_b128 v[146:149], v158 offset:4608
	ds_read_b128 v[150:153], v158 offset:6656
	ds_read_b128 v[154:157], v158 offset:8704
	s_setprio 2
	ds_read_b128 v[158:161], v158 offset:10752
	v_mfma_f32_32x32x16_bf16 v[82:97], v[70:73], v[102:105], v[82:97]
	v_add_f32_e32 v70, v163, v74
	v_add_f32_e32 v70, v164, v70
	s_waitcnt lgkmcnt(0)
	v_mfma_f32_32x32x16_bf16 v[82:97], v[66:69], v[98:101], v[82:97]
	v_add_f32_e32 v66, v165, v70
	v_add_f32_e32 v66, v166, v66
	v_add_f32_e32 v66, v167, v66
	v_add_f32_e32 v66, v168, v66
	v_add_f32_e32 v66, v169, v66
	v_add_f32_e32 v66, v170, v66
	v_add_f32_e32 v202, v171, v66
	v_mfma_f32_32x32x16_bf16 v[66:81], v[138:141], v[118:121], v[34:49]
	v_add_f32_e32 v138, v172, v202
	v_add_f32_e32 v138, v173, v138
	v_add_f32_e32 v138, v174, v138
	v_add_f32_e32 v138, v175, v138
	v_add_f32_e32 v138, v176, v138
	v_add_f32_e32 v138, v177, v138
	v_add_f32_e32 v138, v178, v138
	v_mfma_f32_32x32x16_bf16 v[66:81], v[142:145], v[114:117], v[66:81]
	v_add_f32_e32 v138, v179, v138
	v_add_f32_e32 v138, v180, v138
	v_add_f32_e32 v138, v181, v138
	v_add_f32_e32 v138, v182, v138
	v_add_f32_e32 v138, v183, v138
	v_add_f32_e32 v138, v184, v138
	v_add_f32_e32 v138, v185, v138
	v_mfma_f32_32x32x16_bf16 v[66:81], v[146:149], v[110:113], v[66:81]
	v_add_f32_e32 v138, v186, v138
	v_add_f32_e32 v138, v187, v138
	v_add_f32_e32 v138, v188, v138
	v_add_f32_e32 v138, v189, v138
	v_add_f32_e32 v138, v199, v138
	v_add_f32_e32 v202, v200, v138
	v_cvt_pk_bf16_f32 v138, v137, v162
	v_mfma_f32_32x32x16_bf16 v[66:81], v[150:153], v[106:109], v[66:81]
	v_cvt_pk_bf16_f32 v139, v163, v164
	v_cvt_pk_bf16_f32 v140, v165, v166
	v_cvt_pk_bf16_f32 v141, v167, v168
	v_cvt_pk_bf16_f32 v142, v169, v170
	v_cvt_pk_bf16_f32 v143, v171, v172
	v_cvt_pk_bf16_f32 v144, v173, v174
	v_cvt_pk_bf16_f32 v145, v175, v176
	v_mfma_f32_32x32x16_bf16 v[66:81], v[154:157], v[102:105], v[66:81]
	v_cvt_pk_bf16_f32 v146, v177, v178
	v_cvt_pk_bf16_f32 v147, v179, v180
	v_cvt_pk_bf16_f32 v148, v181, v182
	v_cvt_pk_bf16_f32 v149, v183, v184
	v_cvt_pk_bf16_f32 v150, v185, v186
	v_cvt_pk_bf16_f32 v151, v187, v188
	v_cvt_pk_bf16_f32 v152, v189, v199
	v_mfma_f32_32x32x16_bf16 v[66:81], v[158:161], v[98:101], v[66:81]
	v_cvt_pk_bf16_f32 v153, v200, v201
	v_add_u32_e32 v137, s56, v133
	ds_read_b64_tr_b16 v[154:155], v137 offset:12288
	ds_read_b64_tr_b16 v[156:157], v137 offset:12800
	ds_read_b64_tr_b16 v[158:159], v137 offset:16384
	s_waitcnt lgkmcnt(1)
	v_mfma_f32_32x32x16_bf16 v[18:33], v[154:157], v[138:141], v[18:33]
	ds_read_b64_tr_b16 v[160:161], v137 offset:16896
	ds_read_b64_tr_b16 v[154:155], v137 offset:13312
	s_waitcnt lgkmcnt(1)
	v_mfma_f32_32x32x16_bf16 v[2:17], v[158:161], v[138:141], v[2:17]
	ds_read_b64_tr_b16 v[156:157], v137 offset:13824
	ds_read_b64_tr_b16 v[138:139], v137 offset:17408
	s_waitcnt lgkmcnt(1)
	v_mfma_f32_32x32x16_bf16 v[18:33], v[154:157], v[142:145], v[18:33]
	ds_read_b64_tr_b16 v[140:141], v137 offset:17920
	ds_read_b64_tr_b16 v[154:155], v137 offset:14336
	s_waitcnt lgkmcnt(1)
	s_setprio 1
	v_mfma_f32_32x32x16_bf16 v[2:17], v[138:141], v[142:145], v[2:17]
	ds_read_b64_tr_b16 v[156:157], v137 offset:14848
	ds_read_b64_tr_b16 v[138:139], v137 offset:15360
	ds_read_b64_tr_b16 v[140:141], v137 offset:15872
	ds_read_b64_tr_b16 v[142:143], v137 offset:18432
	ds_read_b64_tr_b16 v[144:145], v137 offset:18944
	ds_read_b64_tr_b16 v[158:159], v137 offset:19456
	ds_read_b64_tr_b16 v[160:161], v137 offset:19968
	v_max_f32_e32 v137, v67, v67
	s_waitcnt lgkmcnt(6)
	v_mfma_f32_32x32x16_bf16 v[18:33], v[154:157], v[146:149], v[18:33]
	v_max_f32_e32 v154, v83, v83
	v_max_f32_e32 v137, v154, v137
	v_max3_f32 v154, v82, v66, v84
	v_max3_f32 v137, v137, v85, v69
	v_max3_f32 v154, v154, v68, v86
	v_max3_f32 v137, v137, v87, v71
	v_max3_f32 v137, v137, v89, v73
	s_waitcnt lgkmcnt(2)
	v_mfma_f32_32x32x16_bf16 v[2:17], v[142:145], v[146:149], v[2:17]
	v_max3_f32 v142, v154, v70, v88
	v_max3_f32 v142, v142, v72, v90
	v_max3_f32 v137, v137, v91, v75
	v_max3_f32 v142, v142, v74, v92
	v_max3_f32 v137, v137, v93, v77
	v_max3_f32 v142, v142, v76, v94
	v_max3_f32 v137, v137, v95, v79
	v_mfma_f32_32x32x16_bf16 v[18:33], v[138:141], v[150:153], v[18:33]
	v_max3_f32 v138, v142, v78, v96
	v_max3_f32 v137, v137, v97, v81
	v_add_f32_e32 v139, v201, v202
	v_max3_f32 v137, v138, v80, v137
	v_add_f32_e32 v136, v136, v139
	v_cmp_lt_f32_e32 vcc, s33, v137
	s_waitcnt lgkmcnt(0)
	v_mfma_f32_32x32x16_bf16 v[2:17], v[158:161], v[150:153], v[2:17]
	s_cbranch_vccz .LBB0_431
	v_mov_b32_e32 v34, v137
	s_nop 1
	v_permlane32_swap_b32 v137, v34
	s_nop 1
	s_nop 0
	v_max3_f32 v36, v137, v34, 0
	v_exp_f32_e64 v38, -v36
	v_add_f32_e32 v135, v135, v36
	v_xor_b32_e32 v34, 0x80000000, v135
	v_pk_add_f32 v[82:83], v[82:83], v[36:37] op_sel_hi:[1,0] neg_lo:[0,1] neg_hi:[0,1]
	v_pk_add_f32 v[84:85], v[84:85], v[36:37] op_sel_hi:[1,0] neg_lo:[0,1] neg_hi:[0,1]
	v_pk_add_f32 v[86:87], v[86:87], v[36:37] op_sel_hi:[1,0] neg_lo:[0,1] neg_hi:[0,1]
	v_pk_add_f32 v[88:89], v[88:89], v[36:37] op_sel_hi:[1,0] neg_lo:[0,1] neg_hi:[0,1]
	v_pk_add_f32 v[90:91], v[90:91], v[36:37] op_sel_hi:[1,0] neg_lo:[0,1] neg_hi:[0,1]
	v_pk_add_f32 v[92:93], v[92:93], v[36:37] op_sel_hi:[1,0] neg_lo:[0,1] neg_hi:[0,1]
	v_pk_add_f32 v[94:95], v[94:95], v[36:37] op_sel_hi:[1,0] neg_lo:[0,1] neg_hi:[0,1]
	v_pk_add_f32 v[96:97], v[96:97], v[36:37] op_sel_hi:[1,0] neg_lo:[0,1] neg_hi:[0,1]
	v_sub_f32_e32 v81, v81, v36
	v_sub_f32_e32 v80, v80, v36
	v_sub_f32_e32 v79, v79, v36
	v_sub_f32_e32 v78, v78, v36
	v_sub_f32_e32 v77, v77, v36
	v_sub_f32_e32 v76, v76, v36
	v_sub_f32_e32 v75, v75, v36
	v_sub_f32_e32 v74, v74, v36
	v_sub_f32_e32 v73, v73, v36
	v_sub_f32_e32 v72, v72, v36
	v_sub_f32_e32 v71, v71, v36
	v_sub_f32_e32 v70, v70, v36
	v_sub_f32_e32 v69, v69, v36
	v_sub_f32_e32 v68, v68, v36
	v_sub_f32_e32 v67, v67, v36
	v_sub_f32_e32 v66, v66, v36
	v_pk_mul_f32 v[32:33], v[32:33], v[38:39] op_sel_hi:[1,0]
	v_pk_mul_f32 v[30:31], v[30:31], v[38:39] op_sel_hi:[1,0]
	v_pk_mul_f32 v[28:29], v[28:29], v[38:39] op_sel_hi:[1,0]
	v_pk_mul_f32 v[26:27], v[26:27], v[38:39] op_sel_hi:[1,0]
	v_pk_mul_f32 v[24:25], v[24:25], v[38:39] op_sel_hi:[1,0]
	v_pk_mul_f32 v[22:23], v[22:23], v[38:39] op_sel_hi:[1,0]
	v_pk_mul_f32 v[20:21], v[20:21], v[38:39] op_sel_hi:[1,0]
	v_pk_mul_f32 v[18:19], v[18:19], v[38:39] op_sel_hi:[1,0]
	v_pk_mul_f32 v[16:17], v[16:17], v[38:39] op_sel_hi:[1,0]
	v_pk_mul_f32 v[14:15], v[14:15], v[38:39] op_sel_hi:[1,0]
	v_pk_mul_f32 v[12:13], v[12:13], v[38:39] op_sel_hi:[1,0]
	v_pk_mul_f32 v[10:11], v[10:11], v[38:39] op_sel_hi:[1,0]
	v_pk_mul_f32 v[8:9], v[8:9], v[38:39] op_sel_hi:[1,0]
	v_pk_mul_f32 v[6:7], v[6:7], v[38:39] op_sel_hi:[1,0]
	v_pk_mul_f32 v[4:5], v[4:5], v[38:39] op_sel_hi:[1,0]
	v_pk_mul_f32 v[2:3], v[2:3], v[38:39] op_sel_hi:[1,0]
	v_mul_f32_e32 v136, v136, v38
	v_mov_b32_e32 v35, v34
	v_mov_b32_e32 v36, v34
	v_mov_b32_e32 v37, v34
	v_mov_b32_e32 v38, v34
	v_mov_b32_e32 v39, v34
	v_mov_b32_e32 v40, v34
	v_mov_b32_e32 v41, v34
	v_mov_b32_e32 v42, v34
	v_mov_b32_e32 v43, v34
	v_mov_b32_e32 v44, v34
	v_mov_b32_e32 v45, v34
	v_mov_b32_e32 v46, v34
	v_mov_b32_e32 v47, v34
	v_mov_b32_e32 v48, v34
	v_mov_b32_e32 v49, v34
	v_mov_b32_e32 v50, v34
	v_mov_b32_e32 v51, v34
	v_mov_b32_e32 v52, v34
	v_mov_b32_e32 v53, v34
	v_mov_b32_e32 v54, v34
	v_mov_b32_e32 v55, v34
	v_mov_b32_e32 v56, v34
	v_mov_b32_e32 v57, v34
	v_mov_b32_e32 v58, v34
	v_mov_b32_e32 v59, v34
	v_mov_b32_e32 v60, v34
	v_mov_b32_e32 v61, v34
	v_mov_b32_e32 v62, v34
	v_mov_b32_e32 v63, v34
	v_mov_b32_e32 v64, v34
	v_mov_b32_e32 v65, v34
.LBB0_431:
	v_exp_f32_e32 v141, v82
	s_setprio 0
	v_exp_f32_e32 v146, v83
	v_exp_f32_e32 v138, v84
	v_exp_f32_e32 v142, v85
	v_exp_f32_e32 v143, v86
	v_exp_f32_e32 v147, v87
	v_exp_f32_e32 v148, v88
	v_exp_f32_e32 v151, v89
	v_exp_f32_e32 v137, v90
	v_exp_f32_e32 v139, v91
	v_exp_f32_e32 v140, v92
	v_exp_f32_e32 v144, v93
	v_exp_f32_e32 v145, v94
	v_exp_f32_e32 v149, v95
	v_exp_f32_e32 v150, v96
	v_exp_f32_e32 v152, v97
	s_mov_b32 s78, s76
	s_waitcnt vmcnt(0)
	s_add_i32 s57, s57, 2
	s_add_i32 s58, s58, 0x80000
	s_cmp_lt_u32 s57, 29
	s_barrier
	s_cbranch_scc0 .LBB0_434
	s_mov_b32 s40, s29
	s_mov_b32 s29, s30
	s_branch .LBB0_422
